# OUT/DOWN: residual (hin) tile lines touched by 4 dummy dword loads per wave before the k-loop tail so the residual epilogue's loads hit L2 instead of exposing miss latency in lockstep
# baseline (speedup 1.0000x reference)
.Lg16_out_k:
	s_add_i32 s9, s3, 2
	s_lshl_b32 s96, s9, 13
	s_add_i32 m0, vcc_lo, 16384
	v_lshl_add_u64 v[160:161], v[188:189], 0, s[96:97]
	global_load_lds_dwordx4 v[160:161], off
	global_load_lds_dwordx4 v[160:161], off offset:1024
	ds_read_b128 v[196:199], v246 offset:0
	ds_read_b128 v[200:203], v162 offset:0
	ds_read_b128 v[204:207], v246 offset:2048
	ds_read_b128 v[242:245], v162 offset:2048
	s_add_i32 s9, s3, 2
	s_lshl_b32 s96, s9, 11
	v_lshl_add_u64 v[248:249], v[184:185], 0, s[96:97]
	v_lshl_add_u64 v[250:251], v[186:187], 0, s[96:97]
	s_waitcnt vmcnt(8) lgkmcnt(3)
	v_mfma_f32_16x16x32_bf16 v[112:115], v[196:199], v[128:131], v[112:115]
	v_mfma_f32_16x16x32_bf16 v[120:123], v[196:199], v[132:135], v[120:123]
	v_mfma_f32_16x16x32_bf16 v[48:51], v[196:199], v[136:139], v[48:51]
	v_mfma_f32_16x16x32_bf16 v[56:59], v[196:199], v[140:143], v[56:59]
	ds_read_b128 v[196:199], v246 offset:4096
	s_waitcnt lgkmcnt(3)
	v_mfma_f32_16x16x32_bf16 v[116:119], v[200:203], v[128:131], v[116:119]
	v_mfma_f32_16x16x32_bf16 v[124:127], v[200:203], v[132:135], v[124:127]
	v_mfma_f32_16x16x32_bf16 v[52:55], v[200:203], v[136:139], v[52:55]
	v_mfma_f32_16x16x32_bf16 v[60:63], v[200:203], v[140:143], v[60:63]
	ds_read_b128 v[200:203], v162 offset:4096
	s_waitcnt lgkmcnt(3)
	v_mfma_f32_16x16x32_bf16 v[96:99], v[204:207], v[128:131], v[96:99]
	v_mfma_f32_16x16x32_bf16 v[104:107], v[204:207], v[132:135], v[104:107]
	v_mfma_f32_16x16x32_bf16 v[32:35], v[204:207], v[136:139], v[32:35]
	v_mfma_f32_16x16x32_bf16 v[40:43], v[204:207], v[140:143], v[40:43]
	ds_read_b128 v[204:207], v246 offset:6144
	s_waitcnt lgkmcnt(3)
	v_mfma_f32_16x16x32_bf16 v[100:103], v[242:245], v[128:131], v[100:103]
	v_mfma_f32_16x16x32_bf16 v[108:111], v[242:245], v[132:135], v[108:111]
	v_mfma_f32_16x16x32_bf16 v[36:39], v[242:245], v[136:139], v[36:39]
	v_mfma_f32_16x16x32_bf16 v[44:47], v[242:245], v[140:143], v[44:47]
	ds_read_b128 v[242:245], v162 offset:6144
	s_waitcnt lgkmcnt(3)
	v_mfma_f32_16x16x32_bf16 v[80:83], v[196:199], v[128:131], v[80:83]
	v_mfma_f32_16x16x32_bf16 v[88:91], v[196:199], v[132:135], v[88:91]
	v_mfma_f32_16x16x32_bf16 v[16:19], v[196:199], v[136:139], v[16:19]
	v_mfma_f32_16x16x32_bf16 v[24:27], v[196:199], v[140:143], v[24:27]
	s_waitcnt lgkmcnt(2)
	v_mfma_f32_16x16x32_bf16 v[84:87], v[200:203], v[128:131], v[84:87]
	v_mfma_f32_16x16x32_bf16 v[92:95], v[200:203], v[132:135], v[92:95]
	v_mfma_f32_16x16x32_bf16 v[20:23], v[200:203], v[136:139], v[20:23]
	v_mfma_f32_16x16x32_bf16 v[28:31], v[200:203], v[140:143], v[28:31]
	s_waitcnt lgkmcnt(1)
	v_mfma_f32_16x16x32_bf16 v[64:67], v[204:207], v[128:131], v[64:67]
	v_mfma_f32_16x16x32_bf16 v[72:75], v[204:207], v[132:135], v[72:75]
	v_mfma_f32_16x16x32_bf16 v[0:3], v[204:207], v[136:139], v[0:3]
	v_mfma_f32_16x16x32_bf16 v[8:11], v[204:207], v[140:143], v[8:11]
	s_waitcnt lgkmcnt(0)
	v_mfma_f32_16x16x32_bf16 v[68:71], v[242:245], v[128:131], v[68:71]
	v_mfma_f32_16x16x32_bf16 v[76:79], v[242:245], v[132:135], v[76:79]
	v_mfma_f32_16x16x32_bf16 v[4:7], v[242:245], v[136:139], v[4:7]
	v_mfma_f32_16x16x32_bf16 v[12:15], v[242:245], v[140:143], v[12:15]
	global_load_dwordx4 v[128:131], v[248:249], off
	global_load_dwordx4 v[132:135], v[248:249], off offset:256
	global_load_dwordx4 v[136:139], v[250:251], off
	global_load_dwordx4 v[140:143], v[250:251], off offset:256
	s_waitcnt vmcnt(10)
	s_barrier
	s_add_i32 s9, s3, 3
	s_lshl_b32 s96, s9, 13
	s_mov_b32 m0, vcc_lo
	v_lshl_add_u64 v[160:161], v[188:189], 0, s[96:97]
	global_load_lds_dwordx4 v[160:161], off
	global_load_lds_dwordx4 v[160:161], off offset:1024
	ds_read_b128 v[196:199], v246 offset:8192
	ds_read_b128 v[200:203], v162 offset:8192
	ds_read_b128 v[204:207], v246 offset:10240
	ds_read_b128 v[242:245], v162 offset:10240
	s_add_i32 s9, s3, 3
	s_lshl_b32 s96, s9, 11
	v_lshl_add_u64 v[248:249], v[184:185], 0, s[96:97]
	v_lshl_add_u64 v[250:251], v[186:187], 0, s[96:97]
	s_waitcnt vmcnt(8) lgkmcnt(3)
	v_mfma_f32_16x16x32_bf16 v[112:115], v[196:199], v[144:147], v[112:115]
	v_mfma_f32_16x16x32_bf16 v[120:123], v[196:199], v[148:151], v[120:123]
	v_mfma_f32_16x16x32_bf16 v[48:51], v[196:199], v[152:155], v[48:51]
	v_mfma_f32_16x16x32_bf16 v[56:59], v[196:199], v[156:159], v[56:59]
	ds_read_b128 v[196:199], v246 offset:12288
	s_waitcnt lgkmcnt(3)
	v_mfma_f32_16x16x32_bf16 v[116:119], v[200:203], v[144:147], v[116:119]
	v_mfma_f32_16x16x32_bf16 v[124:127], v[200:203], v[148:151], v[124:127]
	v_mfma_f32_16x16x32_bf16 v[52:55], v[200:203], v[152:155], v[52:55]
	v_mfma_f32_16x16x32_bf16 v[60:63], v[200:203], v[156:159], v[60:63]
	ds_read_b128 v[200:203], v162 offset:12288
	s_waitcnt lgkmcnt(3)
	v_mfma_f32_16x16x32_bf16 v[96:99], v[204:207], v[144:147], v[96:99]
	v_mfma_f32_16x16x32_bf16 v[104:107], v[204:207], v[148:151], v[104:107]
	v_mfma_f32_16x16x32_bf16 v[32:35], v[204:207], v[152:155], v[32:35]
	v_mfma_f32_16x16x32_bf16 v[40:43], v[204:207], v[156:159], v[40:43]
	ds_read_b128 v[204:207], v246 offset:14336
	s_waitcnt lgkmcnt(3)
	v_mfma_f32_16x16x32_bf16 v[100:103], v[242:245], v[144:147], v[100:103]
	v_mfma_f32_16x16x32_bf16 v[108:111], v[242:245], v[148:151], v[108:111]
	v_mfma_f32_16x16x32_bf16 v[36:39], v[242:245], v[152:155], v[36:39]
	v_mfma_f32_16x16x32_bf16 v[44:47], v[242:245], v[156:159], v[44:47]
	ds_read_b128 v[242:245], v162 offset:14336
	s_waitcnt lgkmcnt(3)
	v_mfma_f32_16x16x32_bf16 v[80:83], v[196:199], v[144:147], v[80:83]
	v_mfma_f32_16x16x32_bf16 v[88:91], v[196:199], v[148:151], v[88:91]
	v_mfma_f32_16x16x32_bf16 v[16:19], v[196:199], v[152:155], v[16:19]
	v_mfma_f32_16x16x32_bf16 v[24:27], v[196:199], v[156:159], v[24:27]
	s_waitcnt lgkmcnt(2)
	v_mfma_f32_16x16x32_bf16 v[84:87], v[200:203], v[144:147], v[84:87]
	v_mfma_f32_16x16x32_bf16 v[92:95], v[200:203], v[148:151], v[92:95]
	v_mfma_f32_16x16x32_bf16 v[20:23], v[200:203], v[152:155], v[20:23]
	v_mfma_f32_16x16x32_bf16 v[28:31], v[200:203], v[156:159], v[28:31]
	s_waitcnt lgkmcnt(1)
	v_mfma_f32_16x16x32_bf16 v[64:67], v[204:207], v[144:147], v[64:67]
	v_mfma_f32_16x16x32_bf16 v[72:75], v[204:207], v[148:151], v[72:75]
	v_mfma_f32_16x16x32_bf16 v[0:3], v[204:207], v[152:155], v[0:3]
	v_mfma_f32_16x16x32_bf16 v[8:11], v[204:207], v[156:159], v[8:11]
	s_waitcnt lgkmcnt(0)
	v_mfma_f32_16x16x32_bf16 v[68:71], v[242:245], v[144:147], v[68:71]
	v_mfma_f32_16x16x32_bf16 v[76:79], v[242:245], v[148:151], v[76:79]
	v_mfma_f32_16x16x32_bf16 v[4:7], v[242:245], v[152:155], v[4:7]
	v_mfma_f32_16x16x32_bf16 v[12:15], v[242:245], v[156:159], v[12:15]
	global_load_dwordx4 v[144:147], v[248:249], off
	global_load_dwordx4 v[148:151], v[248:249], off offset:256
	global_load_dwordx4 v[152:155], v[250:251], off
	global_load_dwordx4 v[156:159], v[250:251], off offset:256
	s_waitcnt vmcnt(10)
	s_barrier
	s_add_i32 s9, s3, 4
	s_lshl_b32 s96, s9, 13
	s_add_i32 m0, vcc_lo, 8192
	v_lshl_add_u64 v[160:161], v[188:189], 0, s[96:97]
	global_load_lds_dwordx4 v[160:161], off
	global_load_lds_dwordx4 v[160:161], off offset:1024
	ds_read_b128 v[196:199], v246 offset:16384
	ds_read_b128 v[200:203], v162 offset:16384
	ds_read_b128 v[204:207], v246 offset:18432
	ds_read_b128 v[242:245], v162 offset:18432
	s_add_i32 s9, s3, 4
	s_lshl_b32 s96, s9, 11
	v_lshl_add_u64 v[248:249], v[184:185], 0, s[96:97]
	v_lshl_add_u64 v[250:251], v[186:187], 0, s[96:97]
	s_waitcnt vmcnt(8) lgkmcnt(3)
	v_mfma_f32_16x16x32_bf16 v[112:115], v[196:199], v[128:131], v[112:115]
	v_mfma_f32_16x16x32_bf16 v[120:123], v[196:199], v[132:135], v[120:123]
	v_mfma_f32_16x16x32_bf16 v[48:51], v[196:199], v[136:139], v[48:51]
	v_mfma_f32_16x16x32_bf16 v[56:59], v[196:199], v[140:143], v[56:59]
	ds_read_b128 v[196:199], v246 offset:20480
	s_waitcnt lgkmcnt(3)
	v_mfma_f32_16x16x32_bf16 v[116:119], v[200:203], v[128:131], v[116:119]
	v_mfma_f32_16x16x32_bf16 v[124:127], v[200:203], v[132:135], v[124:127]
	v_mfma_f32_16x16x32_bf16 v[52:55], v[200:203], v[136:139], v[52:55]
	v_mfma_f32_16x16x32_bf16 v[60:63], v[200:203], v[140:143], v[60:63]
	ds_read_b128 v[200:203], v162 offset:20480
	s_waitcnt lgkmcnt(3)
	v_mfma_f32_16x16x32_bf16 v[96:99], v[204:207], v[128:131], v[96:99]
	v_mfma_f32_16x16x32_bf16 v[104:107], v[204:207], v[132:135], v[104:107]
	v_mfma_f32_16x16x32_bf16 v[32:35], v[204:207], v[136:139], v[32:35]
	v_mfma_f32_16x16x32_bf16 v[40:43], v[204:207], v[140:143], v[40:43]
	ds_read_b128 v[204:207], v246 offset:22528
	s_waitcnt lgkmcnt(3)
	v_mfma_f32_16x16x32_bf16 v[100:103], v[242:245], v[128:131], v[100:103]
	v_mfma_f32_16x16x32_bf16 v[108:111], v[242:245], v[132:135], v[108:111]
	v_mfma_f32_16x16x32_bf16 v[36:39], v[242:245], v[136:139], v[36:39]
	v_mfma_f32_16x16x32_bf16 v[44:47], v[242:245], v[140:143], v[44:47]
	ds_read_b128 v[242:245], v162 offset:22528
	s_waitcnt lgkmcnt(3)
	v_mfma_f32_16x16x32_bf16 v[80:83], v[196:199], v[128:131], v[80:83]
	v_mfma_f32_16x16x32_bf16 v[88:91], v[196:199], v[132:135], v[88:91]
	v_mfma_f32_16x16x32_bf16 v[16:19], v[196:199], v[136:139], v[16:19]
	v_mfma_f32_16x16x32_bf16 v[24:27], v[196:199], v[140:143], v[24:27]
	s_waitcnt lgkmcnt(2)
	v_mfma_f32_16x16x32_bf16 v[84:87], v[200:203], v[128:131], v[84:87]
	v_mfma_f32_16x16x32_bf16 v[92:95], v[200:203], v[132:135], v[92:95]
	v_mfma_f32_16x16x32_bf16 v[20:23], v[200:203], v[136:139], v[20:23]
	v_mfma_f32_16x16x32_bf16 v[28:31], v[200:203], v[140:143], v[28:31]
	s_waitcnt lgkmcnt(1)
	v_mfma_f32_16x16x32_bf16 v[64:67], v[204:207], v[128:131], v[64:67]
	v_mfma_f32_16x16x32_bf16 v[72:75], v[204:207], v[132:135], v[72:75]
	v_mfma_f32_16x16x32_bf16 v[0:3], v[204:207], v[136:139], v[0:3]
	v_mfma_f32_16x16x32_bf16 v[8:11], v[204:207], v[140:143], v[8:11]
	s_waitcnt lgkmcnt(0)
	v_mfma_f32_16x16x32_bf16 v[68:71], v[242:245], v[128:131], v[68:71]
	v_mfma_f32_16x16x32_bf16 v[76:79], v[242:245], v[132:135], v[76:79]
	v_mfma_f32_16x16x32_bf16 v[4:7], v[242:245], v[136:139], v[4:7]
	v_mfma_f32_16x16x32_bf16 v[12:15], v[242:245], v[140:143], v[12:15]
	global_load_dwordx4 v[128:131], v[248:249], off
	global_load_dwordx4 v[132:135], v[248:249], off offset:256
	global_load_dwordx4 v[136:139], v[250:251], off
	global_load_dwordx4 v[140:143], v[250:251], off offset:256
	s_waitcnt vmcnt(10)
	s_barrier
	s_add_i32 s9, s3, 5
	s_lshl_b32 s96, s9, 13
	s_add_i32 m0, vcc_lo, 16384
	v_lshl_add_u64 v[160:161], v[188:189], 0, s[96:97]
	global_load_lds_dwordx4 v[160:161], off
	global_load_lds_dwordx4 v[160:161], off offset:1024
	ds_read_b128 v[196:199], v246 offset:0
	ds_read_b128 v[200:203], v162 offset:0
	ds_read_b128 v[204:207], v246 offset:2048
	ds_read_b128 v[242:245], v162 offset:2048
	s_add_i32 s9, s3, 5
	s_lshl_b32 s96, s9, 11
	v_lshl_add_u64 v[248:249], v[184:185], 0, s[96:97]
	v_lshl_add_u64 v[250:251], v[186:187], 0, s[96:97]
	s_waitcnt vmcnt(8) lgkmcnt(3)
	v_mfma_f32_16x16x32_bf16 v[112:115], v[196:199], v[144:147], v[112:115]
	v_mfma_f32_16x16x32_bf16 v[120:123], v[196:199], v[148:151], v[120:123]
	v_mfma_f32_16x16x32_bf16 v[48:51], v[196:199], v[152:155], v[48:51]
	v_mfma_f32_16x16x32_bf16 v[56:59], v[196:199], v[156:159], v[56:59]
	ds_read_b128 v[196:199], v246 offset:4096
	s_waitcnt lgkmcnt(3)
	v_mfma_f32_16x16x32_bf16 v[116:119], v[200:203], v[144:147], v[116:119]
	v_mfma_f32_16x16x32_bf16 v[124:127], v[200:203], v[148:151], v[124:127]
	v_mfma_f32_16x16x32_bf16 v[52:55], v[200:203], v[152:155], v[52:55]
	v_mfma_f32_16x16x32_bf16 v[60:63], v[200:203], v[156:159], v[60:63]
	ds_read_b128 v[200:203], v162 offset:4096
	s_waitcnt lgkmcnt(3)
	v_mfma_f32_16x16x32_bf16 v[96:99], v[204:207], v[144:147], v[96:99]
	v_mfma_f32_16x16x32_bf16 v[104:107], v[204:207], v[148:151], v[104:107]
	v_mfma_f32_16x16x32_bf16 v[32:35], v[204:207], v[152:155], v[32:35]
	v_mfma_f32_16x16x32_bf16 v[40:43], v[204:207], v[156:159], v[40:43]
	ds_read_b128 v[204:207], v246 offset:6144
	s_waitcnt lgkmcnt(3)
	v_mfma_f32_16x16x32_bf16 v[100:103], v[242:245], v[144:147], v[100:103]
	v_mfma_f32_16x16x32_bf16 v[108:111], v[242:245], v[148:151], v[108:111]
	v_mfma_f32_16x16x32_bf16 v[36:39], v[242:245], v[152:155], v[36:39]
	v_mfma_f32_16x16x32_bf16 v[44:47], v[242:245], v[156:159], v[44:47]
	ds_read_b128 v[242:245], v162 offset:6144
	s_waitcnt lgkmcnt(3)
	v_mfma_f32_16x16x32_bf16 v[80:83], v[196:199], v[144:147], v[80:83]
	v_mfma_f32_16x16x32_bf16 v[88:91], v[196:199], v[148:151], v[88:91]
	v_mfma_f32_16x16x32_bf16 v[16:19], v[196:199], v[152:155], v[16:19]
	v_mfma_f32_16x16x32_bf16 v[24:27], v[196:199], v[156:159], v[24:27]
	s_waitcnt lgkmcnt(2)
	v_mfma_f32_16x16x32_bf16 v[84:87], v[200:203], v[144:147], v[84:87]
	v_mfma_f32_16x16x32_bf16 v[92:95], v[200:203], v[148:151], v[92:95]
	v_mfma_f32_16x16x32_bf16 v[20:23], v[200:203], v[152:155], v[20:23]
	v_mfma_f32_16x16x32_bf16 v[28:31], v[200:203], v[156:159], v[28:31]
	s_waitcnt lgkmcnt(1)
	v_mfma_f32_16x16x32_bf16 v[64:67], v[204:207], v[144:147], v[64:67]
	v_mfma_f32_16x16x32_bf16 v[72:75], v[204:207], v[148:151], v[72:75]
	v_mfma_f32_16x16x32_bf16 v[0:3], v[204:207], v[152:155], v[0:3]
	v_mfma_f32_16x16x32_bf16 v[8:11], v[204:207], v[156:159], v[8:11]
	s_waitcnt lgkmcnt(0)
	v_mfma_f32_16x16x32_bf16 v[68:71], v[242:245], v[144:147], v[68:71]
	v_mfma_f32_16x16x32_bf16 v[76:79], v[242:245], v[148:151], v[76:79]
	v_mfma_f32_16x16x32_bf16 v[4:7], v[242:245], v[152:155], v[4:7]
	v_mfma_f32_16x16x32_bf16 v[12:15], v[242:245], v[156:159], v[12:15]
	global_load_dwordx4 v[144:147], v[248:249], off
	global_load_dwordx4 v[148:151], v[248:249], off offset:256
	global_load_dwordx4 v[152:155], v[250:251], off
	global_load_dwordx4 v[156:159], v[250:251], off offset:256
	s_waitcnt vmcnt(10)
	s_barrier
	s_add_i32 s9, s3, 6
	s_lshl_b32 s96, s9, 13
	s_mov_b32 m0, vcc_lo
	v_lshl_add_u64 v[160:161], v[188:189], 0, s[96:97]
	global_load_lds_dwordx4 v[160:161], off
	global_load_lds_dwordx4 v[160:161], off offset:1024
	ds_read_b128 v[196:199], v246 offset:8192
	ds_read_b128 v[200:203], v162 offset:8192
	ds_read_b128 v[204:207], v246 offset:10240
	ds_read_b128 v[242:245], v162 offset:10240
	s_add_i32 s9, s3, 6
	s_lshl_b32 s96, s9, 11
	v_lshl_add_u64 v[248:249], v[184:185], 0, s[96:97]
	v_lshl_add_u64 v[250:251], v[186:187], 0, s[96:97]
	s_waitcnt vmcnt(8) lgkmcnt(3)
	v_mfma_f32_16x16x32_bf16 v[112:115], v[196:199], v[128:131], v[112:115]
	v_mfma_f32_16x16x32_bf16 v[120:123], v[196:199], v[132:135], v[120:123]
	v_mfma_f32_16x16x32_bf16 v[48:51], v[196:199], v[136:139], v[48:51]
	v_mfma_f32_16x16x32_bf16 v[56:59], v[196:199], v[140:143], v[56:59]
	ds_read_b128 v[196:199], v246 offset:12288
	s_waitcnt lgkmcnt(3)
	v_mfma_f32_16x16x32_bf16 v[116:119], v[200:203], v[128:131], v[116:119]
	v_mfma_f32_16x16x32_bf16 v[124:127], v[200:203], v[132:135], v[124:127]
	v_mfma_f32_16x16x32_bf16 v[52:55], v[200:203], v[136:139], v[52:55]
	v_mfma_f32_16x16x32_bf16 v[60:63], v[200:203], v[140:143], v[60:63]
	ds_read_b128 v[200:203], v162 offset:12288
	s_waitcnt lgkmcnt(3)
	v_mfma_f32_16x16x32_bf16 v[96:99], v[204:207], v[128:131], v[96:99]
	v_mfma_f32_16x16x32_bf16 v[104:107], v[204:207], v[132:135], v[104:107]
	v_mfma_f32_16x16x32_bf16 v[32:35], v[204:207], v[136:139], v[32:35]
	v_mfma_f32_16x16x32_bf16 v[40:43], v[204:207], v[140:143], v[40:43]
	ds_read_b128 v[204:207], v246 offset:14336
	s_waitcnt lgkmcnt(3)
	v_mfma_f32_16x16x32_bf16 v[100:103], v[242:245], v[128:131], v[100:103]
	v_mfma_f32_16x16x32_bf16 v[108:111], v[242:245], v[132:135], v[108:111]
	v_mfma_f32_16x16x32_bf16 v[36:39], v[242:245], v[136:139], v[36:39]
	v_mfma_f32_16x16x32_bf16 v[44:47], v[242:245], v[140:143], v[44:47]
	ds_read_b128 v[242:245], v162 offset:14336
	s_waitcnt lgkmcnt(3)
	v_mfma_f32_16x16x32_bf16 v[80:83], v[196:199], v[128:131], v[80:83]
	v_mfma_f32_16x16x32_bf16 v[88:91], v[196:199], v[132:135], v[88:91]
	v_mfma_f32_16x16x32_bf16 v[16:19], v[196:199], v[136:139], v[16:19]
	v_mfma_f32_16x16x32_bf16 v[24:27], v[196:199], v[140:143], v[24:27]
	s_waitcnt lgkmcnt(2)
	v_mfma_f32_16x16x32_bf16 v[84:87], v[200:203], v[128:131], v[84:87]
	v_mfma_f32_16x16x32_bf16 v[92:95], v[200:203], v[132:135], v[92:95]
	v_mfma_f32_16x16x32_bf16 v[20:23], v[200:203], v[136:139], v[20:23]
	v_mfma_f32_16x16x32_bf16 v[28:31], v[200:203], v[140:143], v[28:31]
	s_waitcnt lgkmcnt(1)
	v_mfma_f32_16x16x32_bf16 v[64:67], v[204:207], v[128:131], v[64:67]
	v_mfma_f32_16x16x32_bf16 v[72:75], v[204:207], v[132:135], v[72:75]
	v_mfma_f32_16x16x32_bf16 v[0:3], v[204:207], v[136:139], v[0:3]
	v_mfma_f32_16x16x32_bf16 v[8:11], v[204:207], v[140:143], v[8:11]
	s_waitcnt lgkmcnt(0)
	v_mfma_f32_16x16x32_bf16 v[68:71], v[242:245], v[128:131], v[68:71]
	v_mfma_f32_16x16x32_bf16 v[76:79], v[242:245], v[132:135], v[76:79]
	v_mfma_f32_16x16x32_bf16 v[4:7], v[242:245], v[136:139], v[4:7]
	v_mfma_f32_16x16x32_bf16 v[12:15], v[242:245], v[140:143], v[12:15]
	global_load_dwordx4 v[128:131], v[248:249], off
	global_load_dwordx4 v[132:135], v[248:249], off offset:256
	global_load_dwordx4 v[136:139], v[250:251], off
	global_load_dwordx4 v[140:143], v[250:251], off offset:256
	s_waitcnt vmcnt(10)
	s_barrier
	s_add_i32 s9, s3, 7
	s_lshl_b32 s96, s9, 13
	s_add_i32 m0, vcc_lo, 8192
	v_lshl_add_u64 v[160:161], v[188:189], 0, s[96:97]
	global_load_lds_dwordx4 v[160:161], off
	global_load_lds_dwordx4 v[160:161], off offset:1024
	ds_read_b128 v[196:199], v246 offset:16384
	ds_read_b128 v[200:203], v162 offset:16384
	ds_read_b128 v[204:207], v246 offset:18432
	ds_read_b128 v[242:245], v162 offset:18432
	s_add_i32 s9, s3, 7
	s_lshl_b32 s96, s9, 11
	v_lshl_add_u64 v[248:249], v[184:185], 0, s[96:97]
	v_lshl_add_u64 v[250:251], v[186:187], 0, s[96:97]
	s_waitcnt vmcnt(8) lgkmcnt(3)
	v_mfma_f32_16x16x32_bf16 v[112:115], v[196:199], v[144:147], v[112:115]
	v_mfma_f32_16x16x32_bf16 v[120:123], v[196:199], v[148:151], v[120:123]
	v_mfma_f32_16x16x32_bf16 v[48:51], v[196:199], v[152:155], v[48:51]
	v_mfma_f32_16x16x32_bf16 v[56:59], v[196:199], v[156:159], v[56:59]
	ds_read_b128 v[196:199], v246 offset:20480
	s_waitcnt lgkmcnt(3)
	v_mfma_f32_16x16x32_bf16 v[116:119], v[200:203], v[144:147], v[116:119]
	v_mfma_f32_16x16x32_bf16 v[124:127], v[200:203], v[148:151], v[124:127]
	v_mfma_f32_16x16x32_bf16 v[52:55], v[200:203], v[152:155], v[52:55]
	v_mfma_f32_16x16x32_bf16 v[60:63], v[200:203], v[156:159], v[60:63]
	ds_read_b128 v[200:203], v162 offset:20480
	s_waitcnt lgkmcnt(3)
	v_mfma_f32_16x16x32_bf16 v[96:99], v[204:207], v[144:147], v[96:99]
	v_mfma_f32_16x16x32_bf16 v[104:107], v[204:207], v[148:151], v[104:107]
	v_mfma_f32_16x16x32_bf16 v[32:35], v[204:207], v[152:155], v[32:35]
	v_mfma_f32_16x16x32_bf16 v[40:43], v[204:207], v[156:159], v[40:43]
	ds_read_b128 v[204:207], v246 offset:22528
	s_waitcnt lgkmcnt(3)
	v_mfma_f32_16x16x32_bf16 v[100:103], v[242:245], v[144:147], v[100:103]
	v_mfma_f32_16x16x32_bf16 v[108:111], v[242:245], v[148:151], v[108:111]
	v_mfma_f32_16x16x32_bf16 v[36:39], v[242:245], v[152:155], v[36:39]
	v_mfma_f32_16x16x32_bf16 v[44:47], v[242:245], v[156:159], v[44:47]
	ds_read_b128 v[242:245], v162 offset:22528
	s_waitcnt lgkmcnt(3)
	v_mfma_f32_16x16x32_bf16 v[80:83], v[196:199], v[144:147], v[80:83]
	v_mfma_f32_16x16x32_bf16 v[88:91], v[196:199], v[148:151], v[88:91]
	v_mfma_f32_16x16x32_bf16 v[16:19], v[196:199], v[152:155], v[16:19]
	v_mfma_f32_16x16x32_bf16 v[24:27], v[196:199], v[156:159], v[24:27]
	s_waitcnt lgkmcnt(2)
	v_mfma_f32_16x16x32_bf16 v[84:87], v[200:203], v[144:147], v[84:87]
	v_mfma_f32_16x16x32_bf16 v[92:95], v[200:203], v[148:151], v[92:95]
	v_mfma_f32_16x16x32_bf16 v[20:23], v[200:203], v[152:155], v[20:23]
	v_mfma_f32_16x16x32_bf16 v[28:31], v[200:203], v[156:159], v[28:31]
	s_waitcnt lgkmcnt(1)
	v_mfma_f32_16x16x32_bf16 v[64:67], v[204:207], v[144:147], v[64:67]
	v_mfma_f32_16x16x32_bf16 v[72:75], v[204:207], v[148:151], v[72:75]
	v_mfma_f32_16x16x32_bf16 v[0:3], v[204:207], v[152:155], v[0:3]
	v_mfma_f32_16x16x32_bf16 v[8:11], v[204:207], v[156:159], v[8:11]
	s_waitcnt lgkmcnt(0)
	v_mfma_f32_16x16x32_bf16 v[68:71], v[242:245], v[144:147], v[68:71]
	v_mfma_f32_16x16x32_bf16 v[76:79], v[242:245], v[148:151], v[76:79]
	v_mfma_f32_16x16x32_bf16 v[4:7], v[242:245], v[152:155], v[4:7]
	v_mfma_f32_16x16x32_bf16 v[12:15], v[242:245], v[156:159], v[12:15]
	global_load_dwordx4 v[144:147], v[248:249], off
	global_load_dwordx4 v[148:151], v[248:249], off offset:256
	global_load_dwordx4 v[152:155], v[250:251], off
	global_load_dwordx4 v[156:159], v[250:251], off offset:256
	s_waitcnt vmcnt(10)
	s_barrier
	s_add_i32 s3, s3, 6
	s_cmp_lt_u32 s3, 30
	s_cbranch_scc1 .Lg16_out_k
	s_lshl_b32 s16, s8, 8
	s_lshl_b32 s18, s2, 9
	v_readlane_b32 s12, v254, 38
	v_readlane_b32 s13, v254, 37
	v_readlane_b32 s22, v254, 40
	v_readlane_b32 s23, v254, 39
	s_add_i32 s17, s16, 0xffff8000
	s_cmpk_lt_u32 s8, 0x80
	s_cselect_b32 s12, s12, s22
	s_cselect_b32 s13, s13, s23
	s_cselect_b32 s16, s16, s17
	s_mov_b32 s17, 0
	s_lshl_b64 s[16:17], s[16:17], 12
	s_add_u32 s16, s16, s18
	s_addc_u32 s17, s17, 0
	s_add_u32 s12, s12, s16
	s_addc_u32 s13, s13, s17
	v_lshlrev_b32_e32 v167, 12, v179
	global_load_dword v163, v167, s[12:13]
	global_load_dword v164, v167, s[12:13] offset:128
	global_load_dword v165, v167, s[12:13] offset:256
	global_load_dword v166, v167, s[12:13] offset:384
	ds_read_b128 v[196:199], v246 offset:0
	ds_read_b128 v[200:203], v162 offset:0
	ds_read_b128 v[204:207], v246 offset:2048
	ds_read_b128 v[242:245], v162 offset:2048
	s_waitcnt vmcnt(10) lgkmcnt(3)
	v_mfma_f32_16x16x32_bf16 v[112:115], v[196:199], v[128:131], v[112:115]
	v_mfma_f32_16x16x32_bf16 v[120:123], v[196:199], v[132:135], v[120:123]
	v_mfma_f32_16x16x32_bf16 v[48:51], v[196:199], v[136:139], v[48:51]
	v_mfma_f32_16x16x32_bf16 v[56:59], v[196:199], v[140:143], v[56:59]
	ds_read_b128 v[196:199], v246 offset:4096
	s_waitcnt lgkmcnt(3)
	v_mfma_f32_16x16x32_bf16 v[116:119], v[200:203], v[128:131], v[116:119]
	v_mfma_f32_16x16x32_bf16 v[124:127], v[200:203], v[132:135], v[124:127]
	v_mfma_f32_16x16x32_bf16 v[52:55], v[200:203], v[136:139], v[52:55]
	v_mfma_f32_16x16x32_bf16 v[60:63], v[200:203], v[140:143], v[60:63]
	ds_read_b128 v[200:203], v162 offset:4096
	s_waitcnt lgkmcnt(3)
	v_mfma_f32_16x16x32_bf16 v[96:99], v[204:207], v[128:131], v[96:99]
	v_mfma_f32_16x16x32_bf16 v[104:107], v[204:207], v[132:135], v[104:107]
	v_mfma_f32_16x16x32_bf16 v[32:35], v[204:207], v[136:139], v[32:35]
	v_mfma_f32_16x16x32_bf16 v[40:43], v[204:207], v[140:143], v[40:43]
	ds_read_b128 v[204:207], v246 offset:6144
	s_waitcnt lgkmcnt(3)
	v_mfma_f32_16x16x32_bf16 v[100:103], v[242:245], v[128:131], v[100:103]
	v_mfma_f32_16x16x32_bf16 v[108:111], v[242:245], v[132:135], v[108:111]
	v_mfma_f32_16x16x32_bf16 v[36:39], v[242:245], v[136:139], v[36:39]
	v_mfma_f32_16x16x32_bf16 v[44:47], v[242:245], v[140:143], v[44:47]
	ds_read_b128 v[242:245], v162 offset:6144
	s_waitcnt lgkmcnt(3)
	v_mfma_f32_16x16x32_bf16 v[80:83], v[196:199], v[128:131], v[80:83]
	v_mfma_f32_16x16x32_bf16 v[88:91], v[196:199], v[132:135], v[88:91]
	v_mfma_f32_16x16x32_bf16 v[16:19], v[196:199], v[136:139], v[16:19]
	v_mfma_f32_16x16x32_bf16 v[24:27], v[196:199], v[140:143], v[24:27]
	s_waitcnt lgkmcnt(2)
	v_mfma_f32_16x16x32_bf16 v[84:87], v[200:203], v[128:131], v[84:87]
	v_mfma_f32_16x16x32_bf16 v[92:95], v[200:203], v[132:135], v[92:95]
	v_mfma_f32_16x16x32_bf16 v[20:23], v[200:203], v[136:139], v[20:23]
	v_mfma_f32_16x16x32_bf16 v[28:31], v[200:203], v[140:143], v[28:31]
	s_waitcnt lgkmcnt(1)
	v_mfma_f32_16x16x32_bf16 v[64:67], v[204:207], v[128:131], v[64:67]
	v_mfma_f32_16x16x32_bf16 v[72:75], v[204:207], v[132:135], v[72:75]
	v_mfma_f32_16x16x32_bf16 v[0:3], v[204:207], v[136:139], v[0:3]
	v_mfma_f32_16x16x32_bf16 v[8:11], v[204:207], v[140:143], v[8:11]
	s_waitcnt lgkmcnt(0)
	v_mfma_f32_16x16x32_bf16 v[68:71], v[242:245], v[128:131], v[68:71]
	v_mfma_f32_16x16x32_bf16 v[76:79], v[242:245], v[132:135], v[76:79]
	v_mfma_f32_16x16x32_bf16 v[4:7], v[242:245], v[136:139], v[4:7]
	v_mfma_f32_16x16x32_bf16 v[12:15], v[242:245], v[140:143], v[12:15]
	s_waitcnt vmcnt(8)
	s_barrier
	ds_read_b128 v[196:199], v246 offset:8192
	ds_read_b128 v[200:203], v162 offset:8192
	ds_read_b128 v[204:207], v246 offset:10240
	ds_read_b128 v[242:245], v162 offset:10240
	s_waitcnt vmcnt(4) lgkmcnt(3)
	v_mfma_f32_16x16x32_bf16 v[112:115], v[196:199], v[144:147], v[112:115]
	v_mfma_f32_16x16x32_bf16 v[120:123], v[196:199], v[148:151], v[120:123]
	v_mfma_f32_16x16x32_bf16 v[48:51], v[196:199], v[152:155], v[48:51]
	v_mfma_f32_16x16x32_bf16 v[56:59], v[196:199], v[156:159], v[56:59]
	ds_read_b128 v[196:199], v246 offset:12288
	s_waitcnt lgkmcnt(3)
	v_mfma_f32_16x16x32_bf16 v[116:119], v[200:203], v[144:147], v[116:119]
	v_mfma_f32_16x16x32_bf16 v[124:127], v[200:203], v[148:151], v[124:127]
	v_mfma_f32_16x16x32_bf16 v[52:55], v[200:203], v[152:155], v[52:55]
	v_mfma_f32_16x16x32_bf16 v[60:63], v[200:203], v[156:159], v[60:63]
	ds_read_b128 v[200:203], v162 offset:12288
	s_waitcnt lgkmcnt(3)
	v_mfma_f32_16x16x32_bf16 v[96:99], v[204:207], v[144:147], v[96:99]
	v_mfma_f32_16x16x32_bf16 v[104:107], v[204:207], v[148:151], v[104:107]
	v_mfma_f32_16x16x32_bf16 v[32:35], v[204:207], v[152:155], v[32:35]
	v_mfma_f32_16x16x32_bf16 v[40:43], v[204:207], v[156:159], v[40:43]
	ds_read_b128 v[204:207], v246 offset:14336
	s_waitcnt lgkmcnt(3)
	v_mfma_f32_16x16x32_bf16 v[100:103], v[242:245], v[144:147], v[100:103]
	v_mfma_f32_16x16x32_bf16 v[108:111], v[242:245], v[148:151], v[108:111]
	v_mfma_f32_16x16x32_bf16 v[36:39], v[242:245], v[152:155], v[36:39]
	v_mfma_f32_16x16x32_bf16 v[44:47], v[242:245], v[156:159], v[44:47]
	ds_read_b128 v[242:245], v162 offset:14336
	s_waitcnt lgkmcnt(3)
	v_mfma_f32_16x16x32_bf16 v[80:83], v[196:199], v[144:147], v[80:83]
	v_mfma_f32_16x16x32_bf16 v[88:91], v[196:199], v[148:151], v[88:91]
	v_mfma_f32_16x16x32_bf16 v[16:19], v[196:199], v[152:155], v[16:19]
	v_mfma_f32_16x16x32_bf16 v[24:27], v[196:199], v[156:159], v[24:27]
	s_waitcnt lgkmcnt(2)
	v_mfma_f32_16x16x32_bf16 v[84:87], v[200:203], v[144:147], v[84:87]
	v_mfma_f32_16x16x32_bf16 v[92:95], v[200:203], v[148:151], v[92:95]
	v_mfma_f32_16x16x32_bf16 v[20:23], v[200:203], v[152:155], v[20:23]
	v_mfma_f32_16x16x32_bf16 v[28:31], v[200:203], v[156:159], v[28:31]
	s_waitcnt lgkmcnt(1)
	v_mfma_f32_16x16x32_bf16 v[64:67], v[204:207], v[144:147], v[64:67]
	v_mfma_f32_16x16x32_bf16 v[72:75], v[204:207], v[148:151], v[72:75]
	v_mfma_f32_16x16x32_bf16 v[0:3], v[204:207], v[152:155], v[0:3]
	v_mfma_f32_16x16x32_bf16 v[8:11], v[204:207], v[156:159], v[8:11]
	s_waitcnt lgkmcnt(0)
	v_mfma_f32_16x16x32_bf16 v[68:71], v[242:245], v[144:147], v[68:71]
	v_mfma_f32_16x16x32_bf16 v[76:79], v[242:245], v[148:151], v[76:79]
	v_mfma_f32_16x16x32_bf16 v[4:7], v[242:245], v[152:155], v[4:7]
	v_mfma_f32_16x16x32_bf16 v[12:15], v[242:245], v[156:159], v[12:15]
	s_barrier
	s_nop 7
	s_nop 1
	s_waitcnt vmcnt(0)
	s_waitcnt vmcnt(0)
	v_and_b32_e32 v188, 63, v179
	v_lshrrev_b32_e32 v189, 6, v179
	v_mul_u32_u24_e32 v249, 0x2400, v189
	v_mov_b32_e32 v250, v249
	v_and_b32_e32 v251, 15, v188
	v_mul_u32_u24_e32 v251, 0x110, v251
	v_add_u32_e32 v249, v249, v251
	v_lshrrev_b32_e32 v251, 4, v188
	v_lshl_add_u32 v249, v251, 5, v249
	v_lshrrev_b32_e32 v237, 4, v188
	v_mul_u32_u24_e32 v251, 0x110, v237
	v_add_u32_e32 v250, v250, v251
	v_and_b32_e32 v251, 15, v188
	v_lshlrev_b32_e32 v251, 4, v251
	v_add_u32_e32 v250, v250, v251
	v_lshl_add_u32 v237, v189, 6, v237
	v_lshl_add_u32 v237, v237, 12, v251
	v_add_u32_e32 v238, 16384, v237
	v_add_u32_e32 v239, 32768, v237
	v_add_u32_e32 v240, 49152, v237
	v_add_u32_e32 v241, 65536, v237
	v_add_u32_e32 v242, 81920, v237
	v_add_u32_e32 v243, 98304, v237
	v_add_u32_e32 v248, 114688, v237
	s_lshl_b32 s16, s8, 8
	s_lshl_b32 s18, s2, 9
	s_lshr_b32 s19, s8, 4
	v_readlane_b32 s12, v254, 38
	v_readlane_b32 s13, v254, 37
	v_readlane_b32 s14, v253, 46
	v_readlane_b32 s15, v253, 47
	v_readlane_b32 s22, v254, 40
	v_readlane_b32 s23, v254, 39
	s_add_i32 s17, s16, 0xffff8000
	s_cmpk_lt_u32 s8, 0x80
	s_cselect_b32 s12, s12, s22
	s_cselect_b32 s13, s13, s23
	s_cselect_b32 s14, s14, s62
	s_cselect_b32 s15, s15, s63
	s_cselect_b32 s19, s19, 8
	s_cselect_b32 s16, s16, s17
	s_mov_b32 s17, 0
	s_lshl_b64 s[16:17], s[16:17], 12
	s_add_u32 s16, s16, s18
	s_addc_u32 s17, s17, 0
	s_add_u32 s12, s12, s16
	s_addc_u32 s13, s13, s17
	s_add_u32 s14, s14, s16
	s_addc_u32 s15, s15, s17
	s_mul_i32 s19, s19, 0x6000
	s_add_u32 s20, s0, s19
	s_addc_u32 s21, s1, 0
	s_add_u32 s20, s20, s18
	s_addc_u32 s21, s21, 0
	global_load_dwordx4 v[244:247], v251, s[20:21]
	global_load_dwordx4 v[160:163], v237, s[12:13]
	global_load_dwordx4 v[164:167], v238, s[12:13]
	global_load_dwordx4 v[168:171], v239, s[12:13]
	global_load_dwordx4 v[172:175], v240, s[12:13]
	global_load_dwordx4 v[196:199], v241, s[12:13]
	global_load_dwordx4 v[200:203], v242, s[12:13]
	global_load_dwordx4 v[204:207], v243, s[12:13]
	global_load_dwordx4 v[184:187], v248, s[12:13]
	ds_write_b128 v249, v[112:115]
	ds_write_b128 v249, v[116:119] offset:16
	ds_write_b128 v249, v[96:99] offset:128
	ds_write_b128 v249, v[100:103] offset:144
	ds_write_b128 v249, v[120:123] offset:4352
	ds_write_b128 v249, v[124:127] offset:4368
	ds_write_b128 v249, v[104:107] offset:4480
	ds_write_b128 v249, v[108:111] offset:4496
	s_waitcnt lgkmcnt(0)
	ds_read_b128 v[128:131], v250
	ds_read_b128 v[132:135], v250 offset:1088
	ds_read_b128 v[136:139], v250 offset:2176
	ds_read_b128 v[140:143], v250 offset:3264
	ds_read_b128 v[144:147], v250 offset:4352
	ds_read_b128 v[148:151], v250 offset:5440
	ds_read_b128 v[152:155], v250 offset:6528
	ds_read_b128 v[156:159], v250 offset:7616
	s_waitcnt vmcnt(7) lgkmcnt(7)
	v_fma_f32 v128, v244, v128, v160
	v_fma_f32 v129, v245, v129, v161
	v_fma_f32 v130, v246, v130, v162
	v_fma_f32 v131, v247, v131, v163
	global_store_dwordx4 v237, v[128:131], s[14:15] sc0 sc1
	s_waitcnt vmcnt(7) lgkmcnt(6)
	v_fma_f32 v132, v244, v132, v164
	v_fma_f32 v133, v245, v133, v165
	v_fma_f32 v134, v246, v134, v166
	v_fma_f32 v135, v247, v135, v167
	global_store_dwordx4 v238, v[132:135], s[14:15] sc0 sc1
	s_waitcnt vmcnt(7) lgkmcnt(5)
	v_fma_f32 v136, v244, v136, v168
	v_fma_f32 v137, v245, v137, v169
	v_fma_f32 v138, v246, v138, v170
	v_fma_f32 v139, v247, v139, v171
	global_store_dwordx4 v239, v[136:139], s[14:15] sc0 sc1
	s_waitcnt vmcnt(7) lgkmcnt(4)
	v_fma_f32 v140, v244, v140, v172
	v_fma_f32 v141, v245, v141, v173
	v_fma_f32 v142, v246, v142, v174
	v_fma_f32 v143, v247, v143, v175
	global_store_dwordx4 v240, v[140:143], s[14:15] sc0 sc1
	s_waitcnt vmcnt(7) lgkmcnt(3)
	v_fma_f32 v144, v244, v144, v196
	v_fma_f32 v145, v245, v145, v197
	v_fma_f32 v146, v246, v146, v198
	v_fma_f32 v147, v247, v147, v199
	global_store_dwordx4 v241, v[144:147], s[14:15] sc0 sc1
	s_waitcnt vmcnt(7) lgkmcnt(2)
	v_fma_f32 v148, v244, v148, v200
	v_fma_f32 v149, v245, v149, v201
	v_fma_f32 v150, v246, v150, v202
	v_fma_f32 v151, v247, v151, v203
	global_store_dwordx4 v242, v[148:151], s[14:15] sc0 sc1
	s_waitcnt vmcnt(7) lgkmcnt(1)
	v_fma_f32 v152, v244, v152, v204
	v_fma_f32 v153, v245, v153, v205
	v_fma_f32 v154, v246, v154, v206
	v_fma_f32 v155, v247, v155, v207
	global_store_dwordx4 v243, v[152:155], s[14:15] sc0 sc1
	s_waitcnt vmcnt(7) lgkmcnt(0)
	v_fma_f32 v156, v244, v156, v184
	v_fma_f32 v157, v245, v157, v185
	v_fma_f32 v158, v246, v158, v186
	v_fma_f32 v159, v247, v159, v187
	global_store_dwordx4 v248, v[156:159], s[14:15] sc0 sc1
	global_load_dwordx4 v[244:247], v251, s[20:21] offset:256
	global_load_dwordx4 v[160:163], v237, s[12:13] offset:256
	global_load_dwordx4 v[164:167], v238, s[12:13] offset:256
	global_load_dwordx4 v[168:171], v239, s[12:13] offset:256
	global_load_dwordx4 v[172:175], v240, s[12:13] offset:256
	global_load_dwordx4 v[196:199], v241, s[12:13] offset:256
	global_load_dwordx4 v[200:203], v242, s[12:13] offset:256
	global_load_dwordx4 v[204:207], v243, s[12:13] offset:256
	global_load_dwordx4 v[184:187], v248, s[12:13] offset:256
	ds_write_b128 v249, v[80:83]
	ds_write_b128 v249, v[84:87] offset:16
	ds_write_b128 v249, v[64:67] offset:128
	ds_write_b128 v249, v[68:71] offset:144
	ds_write_b128 v249, v[88:91] offset:4352
	ds_write_b128 v249, v[92:95] offset:4368
	ds_write_b128 v249, v[72:75] offset:4480
	ds_write_b128 v249, v[76:79] offset:4496
	s_waitcnt lgkmcnt(0)
	ds_read_b128 v[128:131], v250
	ds_read_b128 v[132:135], v250 offset:1088
	ds_read_b128 v[136:139], v250 offset:2176
	ds_read_b128 v[140:143], v250 offset:3264
	ds_read_b128 v[144:147], v250 offset:4352
	ds_read_b128 v[148:151], v250 offset:5440
	ds_read_b128 v[152:155], v250 offset:6528
	ds_read_b128 v[156:159], v250 offset:7616
	s_waitcnt vmcnt(7) lgkmcnt(7)
	v_fma_f32 v128, v244, v128, v160
	v_fma_f32 v129, v245, v129, v161
	v_fma_f32 v130, v246, v130, v162
	v_fma_f32 v131, v247, v131, v163
	global_store_dwordx4 v237, v[128:131], s[14:15] offset:256 sc0 sc1
	s_waitcnt vmcnt(7) lgkmcnt(6)
	v_fma_f32 v132, v244, v132, v164
	v_fma_f32 v133, v245, v133, v165
	v_fma_f32 v134, v246, v134, v166
	v_fma_f32 v135, v247, v135, v167
	global_store_dwordx4 v238, v[132:135], s[14:15] offset:256 sc0 sc1
	s_waitcnt vmcnt(7) lgkmcnt(5)
	v_fma_f32 v136, v244, v136, v168
	v_fma_f32 v137, v245, v137, v169
	v_fma_f32 v138, v246, v138, v170
	v_fma_f32 v139, v247, v139, v171
	global_store_dwordx4 v239, v[136:139], s[14:15] offset:256 sc0 sc1
	s_waitcnt vmcnt(7) lgkmcnt(4)
	v_fma_f32 v140, v244, v140, v172
	v_fma_f32 v141, v245, v141, v173
	v_fma_f32 v142, v246, v142, v174
	v_fma_f32 v143, v247, v143, v175
	global_store_dwordx4 v240, v[140:143], s[14:15] offset:256 sc0 sc1
	s_waitcnt vmcnt(7) lgkmcnt(3)
	v_fma_f32 v144, v244, v144, v196
	v_fma_f32 v145, v245, v145, v197
	v_fma_f32 v146, v246, v146, v198
	v_fma_f32 v147, v247, v147, v199
	global_store_dwordx4 v241, v[144:147], s[14:15] offset:256 sc0 sc1
	s_waitcnt vmcnt(7) lgkmcnt(2)
	v_fma_f32 v148, v244, v148, v200
	v_fma_f32 v149, v245, v149, v201
	v_fma_f32 v150, v246, v150, v202
	v_fma_f32 v151, v247, v151, v203
	global_store_dwordx4 v242, v[148:151], s[14:15] offset:256 sc0 sc1
	s_waitcnt vmcnt(7) lgkmcnt(1)
	v_fma_f32 v152, v244, v152, v204
	v_fma_f32 v153, v245, v153, v205
	v_fma_f32 v154, v246, v154, v206
	v_fma_f32 v155, v247, v155, v207
	global_store_dwordx4 v243, v[152:155], s[14:15] offset:256 sc0 sc1
	s_waitcnt vmcnt(7) lgkmcnt(0)
	v_fma_f32 v156, v244, v156, v184
	v_fma_f32 v157, v245, v157, v185
	v_fma_f32 v158, v246, v158, v186
	v_fma_f32 v159, v247, v159, v187
	global_store_dwordx4 v248, v[156:159], s[14:15] offset:256 sc0 sc1
	s_add_u32 s12, s12, 0x20000
	s_addc_u32 s13, s13, 0
	s_add_u32 s14, s14, 0x20000
	s_addc_u32 s15, s15, 0
	global_load_dwordx4 v[244:247], v251, s[20:21]
	global_load_dwordx4 v[160:163], v237, s[12:13]
	global_load_dwordx4 v[164:167], v238, s[12:13]
	global_load_dwordx4 v[168:171], v239, s[12:13]
	global_load_dwordx4 v[172:175], v240, s[12:13]
	global_load_dwordx4 v[196:199], v241, s[12:13]
	global_load_dwordx4 v[200:203], v242, s[12:13]
	global_load_dwordx4 v[204:207], v243, s[12:13]
	global_load_dwordx4 v[184:187], v248, s[12:13]
	ds_write_b128 v249, v[48:51]
	ds_write_b128 v249, v[52:55] offset:16
	ds_write_b128 v249, v[32:35] offset:128
	ds_write_b128 v249, v[36:39] offset:144
	ds_write_b128 v249, v[56:59] offset:4352
	ds_write_b128 v249, v[60:63] offset:4368
	ds_write_b128 v249, v[40:43] offset:4480
	ds_write_b128 v249, v[44:47] offset:4496
	s_waitcnt lgkmcnt(0)
	ds_read_b128 v[128:131], v250
	ds_read_b128 v[132:135], v250 offset:1088
	ds_read_b128 v[136:139], v250 offset:2176
	ds_read_b128 v[140:143], v250 offset:3264
	ds_read_b128 v[144:147], v250 offset:4352
	ds_read_b128 v[148:151], v250 offset:5440
	ds_read_b128 v[152:155], v250 offset:6528
	ds_read_b128 v[156:159], v250 offset:7616
	s_waitcnt vmcnt(7) lgkmcnt(7)
	v_fma_f32 v128, v244, v128, v160
	v_fma_f32 v129, v245, v129, v161
	v_fma_f32 v130, v246, v130, v162
	v_fma_f32 v131, v247, v131, v163
	global_store_dwordx4 v237, v[128:131], s[14:15] sc0 sc1
	s_waitcnt vmcnt(7) lgkmcnt(6)
	v_fma_f32 v132, v244, v132, v164
	v_fma_f32 v133, v245, v133, v165
	v_fma_f32 v134, v246, v134, v166
	v_fma_f32 v135, v247, v135, v167
	global_store_dwordx4 v238, v[132:135], s[14:15] sc0 sc1
	s_waitcnt vmcnt(7) lgkmcnt(5)
	v_fma_f32 v136, v244, v136, v168
	v_fma_f32 v137, v245, v137, v169
	v_fma_f32 v138, v246, v138, v170
	v_fma_f32 v139, v247, v139, v171
	global_store_dwordx4 v239, v[136:139], s[14:15] sc0 sc1
	s_waitcnt vmcnt(7) lgkmcnt(4)
	v_fma_f32 v140, v244, v140, v172
	v_fma_f32 v141, v245, v141, v173
	v_fma_f32 v142, v246, v142, v174
	v_fma_f32 v143, v247, v143, v175
	global_store_dwordx4 v240, v[140:143], s[14:15] sc0 sc1
	s_waitcnt vmcnt(7) lgkmcnt(3)
	v_fma_f32 v144, v244, v144, v196
	v_fma_f32 v145, v245, v145, v197
	v_fma_f32 v146, v246, v146, v198
	v_fma_f32 v147, v247, v147, v199
	global_store_dwordx4 v241, v[144:147], s[14:15] sc0 sc1
	s_waitcnt vmcnt(7) lgkmcnt(2)
	v_fma_f32 v148, v244, v148, v200
	v_fma_f32 v149, v245, v149, v201
	v_fma_f32 v150, v246, v150, v202
	v_fma_f32 v151, v247, v151, v203
	global_store_dwordx4 v242, v[148:151], s[14:15] sc0 sc1
	s_waitcnt vmcnt(7) lgkmcnt(1)
	v_fma_f32 v152, v244, v152, v204
	v_fma_f32 v153, v245, v153, v205
	v_fma_f32 v154, v246, v154, v206
	v_fma_f32 v155, v247, v155, v207
	global_store_dwordx4 v243, v[152:155], s[14:15] sc0 sc1
	s_waitcnt vmcnt(7) lgkmcnt(0)
	v_fma_f32 v156, v244, v156, v184
	v_fma_f32 v157, v245, v157, v185
	v_fma_f32 v158, v246, v158, v186
	v_fma_f32 v159, v247, v159, v187
	global_store_dwordx4 v248, v[156:159], s[14:15] sc0 sc1
	global_load_dwordx4 v[244:247], v251, s[20:21] offset:256
	global_load_dwordx4 v[160:163], v237, s[12:13] offset:256
	global_load_dwordx4 v[164:167], v238, s[12:13] offset:256
	global_load_dwordx4 v[168:171], v239, s[12:13] offset:256
	global_load_dwordx4 v[172:175], v240, s[12:13] offset:256
	global_load_dwordx4 v[196:199], v241, s[12:13] offset:256
	global_load_dwordx4 v[200:203], v242, s[12:13] offset:256
	global_load_dwordx4 v[204:207], v243, s[12:13] offset:256
	global_load_dwordx4 v[184:187], v248, s[12:13] offset:256
	ds_write_b128 v249, v[16:19]
	ds_write_b128 v249, v[20:23] offset:16
	ds_write_b128 v249, v[0:3] offset:128
	ds_write_b128 v249, v[4:7] offset:144
	ds_write_b128 v249, v[24:27] offset:4352
	ds_write_b128 v249, v[28:31] offset:4368
	ds_write_b128 v249, v[8:11] offset:4480
	ds_write_b128 v249, v[12:15] offset:4496
	s_waitcnt lgkmcnt(0)
	ds_read_b128 v[128:131], v250
	ds_read_b128 v[132:135], v250 offset:1088
	ds_read_b128 v[136:139], v250 offset:2176
	ds_read_b128 v[140:143], v250 offset:3264
	ds_read_b128 v[144:147], v250 offset:4352
	ds_read_b128 v[148:151], v250 offset:5440
	ds_read_b128 v[152:155], v250 offset:6528
	ds_read_b128 v[156:159], v250 offset:7616
	s_waitcnt vmcnt(7) lgkmcnt(7)
	v_fma_f32 v128, v244, v128, v160
	v_fma_f32 v129, v245, v129, v161
	v_fma_f32 v130, v246, v130, v162
	v_fma_f32 v131, v247, v131, v163
	global_store_dwordx4 v237, v[128:131], s[14:15] offset:256 sc0 sc1
	s_waitcnt vmcnt(7) lgkmcnt(6)
	v_fma_f32 v132, v244, v132, v164
	v_fma_f32 v133, v245, v133, v165
	v_fma_f32 v134, v246, v134, v166
	v_fma_f32 v135, v247, v135, v167
	global_store_dwordx4 v238, v[132:135], s[14:15] offset:256 sc0 sc1
	s_waitcnt vmcnt(7) lgkmcnt(5)
	v_fma_f32 v136, v244, v136, v168
	v_fma_f32 v137, v245, v137, v169
	v_fma_f32 v138, v246, v138, v170
	v_fma_f32 v139, v247, v139, v171
	global_store_dwordx4 v239, v[136:139], s[14:15] offset:256 sc0 sc1
	s_waitcnt vmcnt(7) lgkmcnt(4)
	v_fma_f32 v140, v244, v140, v172
	v_fma_f32 v141, v245, v141, v173
	v_fma_f32 v142, v246, v142, v174
	v_fma_f32 v143, v247, v143, v175
	global_store_dwordx4 v240, v[140:143], s[14:15] offset:256 sc0 sc1
	s_waitcnt vmcnt(7) lgkmcnt(3)
	v_fma_f32 v144, v244, v144, v196
	v_fma_f32 v145, v245, v145, v197
	v_fma_f32 v146, v246, v146, v198
	v_fma_f32 v147, v247, v147, v199
	global_store_dwordx4 v241, v[144:147], s[14:15] offset:256 sc0 sc1
	s_waitcnt vmcnt(7) lgkmcnt(2)
	v_fma_f32 v148, v244, v148, v200
	v_fma_f32 v149, v245, v149, v201
	v_fma_f32 v150, v246, v150, v202
	v_fma_f32 v151, v247, v151, v203
	global_store_dwordx4 v242, v[148:151], s[14:15] offset:256 sc0 sc1
	s_waitcnt vmcnt(7) lgkmcnt(1)
	v_fma_f32 v152, v244, v152, v204
	v_fma_f32 v153, v245, v153, v205
	v_fma_f32 v154, v246, v154, v206
	v_fma_f32 v155, v247, v155, v207
	global_store_dwordx4 v243, v[152:155], s[14:15] offset:256 sc0 sc1
	s_waitcnt vmcnt(7) lgkmcnt(0)
	v_fma_f32 v156, v244, v156, v184
	v_fma_f32 v157, v245, v157, v185
	v_fma_f32 v158, v246, v158, v186
	v_fma_f32 v159, v247, v159, v187
	global_store_dwordx4 v248, v[156:159], s[14:15] offset:256 sc0 sc1
	s_waitcnt lgkmcnt(0)
	v_readlane_b32 s16, v254, 11
	s_andn2_b32 s17, s26, 63
	s_add_i32 s4, s4, s16
	s_cmp_lt_i32 s4, s17
	s_cbranch_scc0 .Lhx_out_left
	s_barrier
	s_branch .LBB0_923

.Lg16_outh_k:
	s_add_i32 s9, s3, 2
	s_lshl_b32 s96, s9, 13
	s_add_i32 m0, vcc_lo, 16384
	v_lshl_add_u64 v[160:161], v[188:189], 0, s[96:97]
	global_load_lds_dwordx4 v[160:161], off
	global_load_lds_dwordx4 v[160:161], off offset:1024
	ds_read_b128 v[196:199], v246 offset:0
	ds_read_b128 v[200:203], v162 offset:0
	ds_read_b128 v[204:207], v246 offset:2048
	ds_read_b128 v[242:245], v162 offset:2048
	s_add_i32 s9, s3, 2
	s_lshl_b32 s96, s9, 11
	v_lshl_add_u64 v[248:249], v[184:185], 0, s[96:97]
	v_lshl_add_u64 v[250:251], v[186:187], 0, s[96:97]
	s_waitcnt vmcnt(6) lgkmcnt(3)
	v_mfma_f32_16x16x32_bf16 v[112:115], v[196:199], v[128:131], v[112:115]
	v_mfma_f32_16x16x32_bf16 v[120:123], v[196:199], v[132:135], v[120:123]
	ds_read_b128 v[196:199], v246 offset:4096
	s_waitcnt lgkmcnt(3)
	v_mfma_f32_16x16x32_bf16 v[116:119], v[200:203], v[128:131], v[116:119]
	v_mfma_f32_16x16x32_bf16 v[124:127], v[200:203], v[132:135], v[124:127]
	ds_read_b128 v[200:203], v162 offset:4096
	s_waitcnt lgkmcnt(3)
	v_mfma_f32_16x16x32_bf16 v[96:99], v[204:207], v[128:131], v[96:99]
	v_mfma_f32_16x16x32_bf16 v[104:107], v[204:207], v[132:135], v[104:107]
	ds_read_b128 v[204:207], v246 offset:6144
	s_waitcnt lgkmcnt(3)
	v_mfma_f32_16x16x32_bf16 v[100:103], v[242:245], v[128:131], v[100:103]
	v_mfma_f32_16x16x32_bf16 v[108:111], v[242:245], v[132:135], v[108:111]
	ds_read_b128 v[242:245], v162 offset:6144
	s_waitcnt lgkmcnt(3)
	v_mfma_f32_16x16x32_bf16 v[80:83], v[196:199], v[128:131], v[80:83]
	v_mfma_f32_16x16x32_bf16 v[88:91], v[196:199], v[132:135], v[88:91]
	s_waitcnt lgkmcnt(2)
	v_mfma_f32_16x16x32_bf16 v[84:87], v[200:203], v[128:131], v[84:87]
	v_mfma_f32_16x16x32_bf16 v[92:95], v[200:203], v[132:135], v[92:95]
	s_waitcnt lgkmcnt(1)
	v_mfma_f32_16x16x32_bf16 v[64:67], v[204:207], v[128:131], v[64:67]
	v_mfma_f32_16x16x32_bf16 v[72:75], v[204:207], v[132:135], v[72:75]
	s_waitcnt lgkmcnt(0)
	v_mfma_f32_16x16x32_bf16 v[68:71], v[242:245], v[128:131], v[68:71]
	v_mfma_f32_16x16x32_bf16 v[76:79], v[242:245], v[132:135], v[76:79]
	global_load_dwordx4 v[128:131], v[248:249], off
	global_load_dwordx4 v[132:135], v[248:249], off offset:256
	s_waitcnt vmcnt(6)
	s_barrier
	s_add_i32 s9, s3, 3
	s_lshl_b32 s96, s9, 13
	s_mov_b32 m0, vcc_lo
	v_lshl_add_u64 v[160:161], v[188:189], 0, s[96:97]
	global_load_lds_dwordx4 v[160:161], off
	global_load_lds_dwordx4 v[160:161], off offset:1024
	ds_read_b128 v[196:199], v246 offset:8192
	ds_read_b128 v[200:203], v162 offset:8192
	ds_read_b128 v[204:207], v246 offset:10240
	ds_read_b128 v[242:245], v162 offset:10240
	s_add_i32 s9, s3, 3
	s_lshl_b32 s96, s9, 11
	v_lshl_add_u64 v[248:249], v[184:185], 0, s[96:97]
	v_lshl_add_u64 v[250:251], v[186:187], 0, s[96:97]
	s_waitcnt vmcnt(6) lgkmcnt(3)
	v_mfma_f32_16x16x32_bf16 v[112:115], v[196:199], v[144:147], v[112:115]
	v_mfma_f32_16x16x32_bf16 v[120:123], v[196:199], v[148:151], v[120:123]
	ds_read_b128 v[196:199], v246 offset:12288
	s_waitcnt lgkmcnt(3)
	v_mfma_f32_16x16x32_bf16 v[116:119], v[200:203], v[144:147], v[116:119]
	v_mfma_f32_16x16x32_bf16 v[124:127], v[200:203], v[148:151], v[124:127]
	ds_read_b128 v[200:203], v162 offset:12288
	s_waitcnt lgkmcnt(3)
	v_mfma_f32_16x16x32_bf16 v[96:99], v[204:207], v[144:147], v[96:99]
	v_mfma_f32_16x16x32_bf16 v[104:107], v[204:207], v[148:151], v[104:107]
	ds_read_b128 v[204:207], v246 offset:14336
	s_waitcnt lgkmcnt(3)
	v_mfma_f32_16x16x32_bf16 v[100:103], v[242:245], v[144:147], v[100:103]
	v_mfma_f32_16x16x32_bf16 v[108:111], v[242:245], v[148:151], v[108:111]
	ds_read_b128 v[242:245], v162 offset:14336
	s_waitcnt lgkmcnt(3)
	v_mfma_f32_16x16x32_bf16 v[80:83], v[196:199], v[144:147], v[80:83]
	v_mfma_f32_16x16x32_bf16 v[88:91], v[196:199], v[148:151], v[88:91]
	s_waitcnt lgkmcnt(2)
	v_mfma_f32_16x16x32_bf16 v[84:87], v[200:203], v[144:147], v[84:87]
	v_mfma_f32_16x16x32_bf16 v[92:95], v[200:203], v[148:151], v[92:95]
	s_waitcnt lgkmcnt(1)
	v_mfma_f32_16x16x32_bf16 v[64:67], v[204:207], v[144:147], v[64:67]
	v_mfma_f32_16x16x32_bf16 v[72:75], v[204:207], v[148:151], v[72:75]
	s_waitcnt lgkmcnt(0)
	v_mfma_f32_16x16x32_bf16 v[68:71], v[242:245], v[144:147], v[68:71]
	v_mfma_f32_16x16x32_bf16 v[76:79], v[242:245], v[148:151], v[76:79]
	global_load_dwordx4 v[144:147], v[248:249], off
	global_load_dwordx4 v[148:151], v[248:249], off offset:256
	s_waitcnt vmcnt(6)
	s_barrier
	s_add_i32 s9, s3, 4
	s_lshl_b32 s96, s9, 13
	s_add_i32 m0, vcc_lo, 8192
	v_lshl_add_u64 v[160:161], v[188:189], 0, s[96:97]
	global_load_lds_dwordx4 v[160:161], off
	global_load_lds_dwordx4 v[160:161], off offset:1024
	ds_read_b128 v[196:199], v246 offset:16384
	ds_read_b128 v[200:203], v162 offset:16384
	ds_read_b128 v[204:207], v246 offset:18432
	ds_read_b128 v[242:245], v162 offset:18432
	s_add_i32 s9, s3, 4
	s_lshl_b32 s96, s9, 11
	v_lshl_add_u64 v[248:249], v[184:185], 0, s[96:97]
	v_lshl_add_u64 v[250:251], v[186:187], 0, s[96:97]
	s_waitcnt vmcnt(6) lgkmcnt(3)
	v_mfma_f32_16x16x32_bf16 v[112:115], v[196:199], v[128:131], v[112:115]
	v_mfma_f32_16x16x32_bf16 v[120:123], v[196:199], v[132:135], v[120:123]
	ds_read_b128 v[196:199], v246 offset:20480
	s_waitcnt lgkmcnt(3)
	v_mfma_f32_16x16x32_bf16 v[116:119], v[200:203], v[128:131], v[116:119]
	v_mfma_f32_16x16x32_bf16 v[124:127], v[200:203], v[132:135], v[124:127]
	ds_read_b128 v[200:203], v162 offset:20480
	s_waitcnt lgkmcnt(3)
	v_mfma_f32_16x16x32_bf16 v[96:99], v[204:207], v[128:131], v[96:99]
	v_mfma_f32_16x16x32_bf16 v[104:107], v[204:207], v[132:135], v[104:107]
	ds_read_b128 v[204:207], v246 offset:22528
	s_waitcnt lgkmcnt(3)
	v_mfma_f32_16x16x32_bf16 v[100:103], v[242:245], v[128:131], v[100:103]
	v_mfma_f32_16x16x32_bf16 v[108:111], v[242:245], v[132:135], v[108:111]
	ds_read_b128 v[242:245], v162 offset:22528
	s_waitcnt lgkmcnt(3)
	v_mfma_f32_16x16x32_bf16 v[80:83], v[196:199], v[128:131], v[80:83]
	v_mfma_f32_16x16x32_bf16 v[88:91], v[196:199], v[132:135], v[88:91]
	s_waitcnt lgkmcnt(2)
	v_mfma_f32_16x16x32_bf16 v[84:87], v[200:203], v[128:131], v[84:87]
	v_mfma_f32_16x16x32_bf16 v[92:95], v[200:203], v[132:135], v[92:95]
	s_waitcnt lgkmcnt(1)
	v_mfma_f32_16x16x32_bf16 v[64:67], v[204:207], v[128:131], v[64:67]
	v_mfma_f32_16x16x32_bf16 v[72:75], v[204:207], v[132:135], v[72:75]
	s_waitcnt lgkmcnt(0)
	v_mfma_f32_16x16x32_bf16 v[68:71], v[242:245], v[128:131], v[68:71]
	v_mfma_f32_16x16x32_bf16 v[76:79], v[242:245], v[132:135], v[76:79]
	global_load_dwordx4 v[128:131], v[248:249], off
	global_load_dwordx4 v[132:135], v[248:249], off offset:256
	s_waitcnt vmcnt(6)
	s_barrier
	s_add_i32 s9, s3, 5
	s_lshl_b32 s96, s9, 13
	s_add_i32 m0, vcc_lo, 16384
	v_lshl_add_u64 v[160:161], v[188:189], 0, s[96:97]
	global_load_lds_dwordx4 v[160:161], off
	global_load_lds_dwordx4 v[160:161], off offset:1024
	ds_read_b128 v[196:199], v246 offset:0
	ds_read_b128 v[200:203], v162 offset:0
	ds_read_b128 v[204:207], v246 offset:2048
	ds_read_b128 v[242:245], v162 offset:2048
	s_add_i32 s9, s3, 5
	s_lshl_b32 s96, s9, 11
	v_lshl_add_u64 v[248:249], v[184:185], 0, s[96:97]
	v_lshl_add_u64 v[250:251], v[186:187], 0, s[96:97]
	s_waitcnt vmcnt(6) lgkmcnt(3)
	v_mfma_f32_16x16x32_bf16 v[112:115], v[196:199], v[144:147], v[112:115]
	v_mfma_f32_16x16x32_bf16 v[120:123], v[196:199], v[148:151], v[120:123]
	ds_read_b128 v[196:199], v246 offset:4096
	s_waitcnt lgkmcnt(3)
	v_mfma_f32_16x16x32_bf16 v[116:119], v[200:203], v[144:147], v[116:119]
	v_mfma_f32_16x16x32_bf16 v[124:127], v[200:203], v[148:151], v[124:127]
	ds_read_b128 v[200:203], v162 offset:4096
	s_waitcnt lgkmcnt(3)
	v_mfma_f32_16x16x32_bf16 v[96:99], v[204:207], v[144:147], v[96:99]
	v_mfma_f32_16x16x32_bf16 v[104:107], v[204:207], v[148:151], v[104:107]
	ds_read_b128 v[204:207], v246 offset:6144
	s_waitcnt lgkmcnt(3)
	v_mfma_f32_16x16x32_bf16 v[100:103], v[242:245], v[144:147], v[100:103]
	v_mfma_f32_16x16x32_bf16 v[108:111], v[242:245], v[148:151], v[108:111]
	ds_read_b128 v[242:245], v162 offset:6144
	s_waitcnt lgkmcnt(3)
	v_mfma_f32_16x16x32_bf16 v[80:83], v[196:199], v[144:147], v[80:83]
	v_mfma_f32_16x16x32_bf16 v[88:91], v[196:199], v[148:151], v[88:91]
	s_waitcnt lgkmcnt(2)
	v_mfma_f32_16x16x32_bf16 v[84:87], v[200:203], v[144:147], v[84:87]
	v_mfma_f32_16x16x32_bf16 v[92:95], v[200:203], v[148:151], v[92:95]
	s_waitcnt lgkmcnt(1)
	v_mfma_f32_16x16x32_bf16 v[64:67], v[204:207], v[144:147], v[64:67]
	v_mfma_f32_16x16x32_bf16 v[72:75], v[204:207], v[148:151], v[72:75]
	s_waitcnt lgkmcnt(0)
	v_mfma_f32_16x16x32_bf16 v[68:71], v[242:245], v[144:147], v[68:71]
	v_mfma_f32_16x16x32_bf16 v[76:79], v[242:245], v[148:151], v[76:79]
	global_load_dwordx4 v[144:147], v[248:249], off
	global_load_dwordx4 v[148:151], v[248:249], off offset:256
	s_waitcnt vmcnt(6)
	s_barrier
	s_add_i32 s9, s3, 6
	s_lshl_b32 s96, s9, 13
	s_mov_b32 m0, vcc_lo
	v_lshl_add_u64 v[160:161], v[188:189], 0, s[96:97]
	global_load_lds_dwordx4 v[160:161], off
	global_load_lds_dwordx4 v[160:161], off offset:1024
	ds_read_b128 v[196:199], v246 offset:8192
	ds_read_b128 v[200:203], v162 offset:8192
	ds_read_b128 v[204:207], v246 offset:10240
	ds_read_b128 v[242:245], v162 offset:10240
	s_add_i32 s9, s3, 6
	s_lshl_b32 s96, s9, 11
	v_lshl_add_u64 v[248:249], v[184:185], 0, s[96:97]
	v_lshl_add_u64 v[250:251], v[186:187], 0, s[96:97]
	s_waitcnt vmcnt(6) lgkmcnt(3)
	v_mfma_f32_16x16x32_bf16 v[112:115], v[196:199], v[128:131], v[112:115]
	v_mfma_f32_16x16x32_bf16 v[120:123], v[196:199], v[132:135], v[120:123]
	ds_read_b128 v[196:199], v246 offset:12288
	s_waitcnt lgkmcnt(3)
	v_mfma_f32_16x16x32_bf16 v[116:119], v[200:203], v[128:131], v[116:119]
	v_mfma_f32_16x16x32_bf16 v[124:127], v[200:203], v[132:135], v[124:127]
	ds_read_b128 v[200:203], v162 offset:12288
	s_waitcnt lgkmcnt(3)
	v_mfma_f32_16x16x32_bf16 v[96:99], v[204:207], v[128:131], v[96:99]
	v_mfma_f32_16x16x32_bf16 v[104:107], v[204:207], v[132:135], v[104:107]
	ds_read_b128 v[204:207], v246 offset:14336
	s_waitcnt lgkmcnt(3)
	v_mfma_f32_16x16x32_bf16 v[100:103], v[242:245], v[128:131], v[100:103]
	v_mfma_f32_16x16x32_bf16 v[108:111], v[242:245], v[132:135], v[108:111]
	ds_read_b128 v[242:245], v162 offset:14336
	s_waitcnt lgkmcnt(3)
	v_mfma_f32_16x16x32_bf16 v[80:83], v[196:199], v[128:131], v[80:83]
	v_mfma_f32_16x16x32_bf16 v[88:91], v[196:199], v[132:135], v[88:91]
	s_waitcnt lgkmcnt(2)
	v_mfma_f32_16x16x32_bf16 v[84:87], v[200:203], v[128:131], v[84:87]
	v_mfma_f32_16x16x32_bf16 v[92:95], v[200:203], v[132:135], v[92:95]
	s_waitcnt lgkmcnt(1)
	v_mfma_f32_16x16x32_bf16 v[64:67], v[204:207], v[128:131], v[64:67]
	v_mfma_f32_16x16x32_bf16 v[72:75], v[204:207], v[132:135], v[72:75]
	s_waitcnt lgkmcnt(0)
	v_mfma_f32_16x16x32_bf16 v[68:71], v[242:245], v[128:131], v[68:71]
	v_mfma_f32_16x16x32_bf16 v[76:79], v[242:245], v[132:135], v[76:79]
	global_load_dwordx4 v[128:131], v[248:249], off
	global_load_dwordx4 v[132:135], v[248:249], off offset:256
	s_waitcnt vmcnt(6)
	s_barrier
	s_add_i32 s9, s3, 7
	s_lshl_b32 s96, s9, 13
	s_add_i32 m0, vcc_lo, 8192
	v_lshl_add_u64 v[160:161], v[188:189], 0, s[96:97]
	global_load_lds_dwordx4 v[160:161], off
	global_load_lds_dwordx4 v[160:161], off offset:1024
	ds_read_b128 v[196:199], v246 offset:16384
	ds_read_b128 v[200:203], v162 offset:16384
	ds_read_b128 v[204:207], v246 offset:18432
	ds_read_b128 v[242:245], v162 offset:18432
	s_add_i32 s9, s3, 7
	s_lshl_b32 s96, s9, 11
	v_lshl_add_u64 v[248:249], v[184:185], 0, s[96:97]
	v_lshl_add_u64 v[250:251], v[186:187], 0, s[96:97]
	s_waitcnt vmcnt(6) lgkmcnt(3)
	v_mfma_f32_16x16x32_bf16 v[112:115], v[196:199], v[144:147], v[112:115]
	v_mfma_f32_16x16x32_bf16 v[120:123], v[196:199], v[148:151], v[120:123]
	ds_read_b128 v[196:199], v246 offset:20480
	s_waitcnt lgkmcnt(3)
	v_mfma_f32_16x16x32_bf16 v[116:119], v[200:203], v[144:147], v[116:119]
	v_mfma_f32_16x16x32_bf16 v[124:127], v[200:203], v[148:151], v[124:127]
	ds_read_b128 v[200:203], v162 offset:20480
	s_waitcnt lgkmcnt(3)
	v_mfma_f32_16x16x32_bf16 v[96:99], v[204:207], v[144:147], v[96:99]
	v_mfma_f32_16x16x32_bf16 v[104:107], v[204:207], v[148:151], v[104:107]
	ds_read_b128 v[204:207], v246 offset:22528
	s_waitcnt lgkmcnt(3)
	v_mfma_f32_16x16x32_bf16 v[100:103], v[242:245], v[144:147], v[100:103]
	v_mfma_f32_16x16x32_bf16 v[108:111], v[242:245], v[148:151], v[108:111]
	ds_read_b128 v[242:245], v162 offset:22528
	s_waitcnt lgkmcnt(3)
	v_mfma_f32_16x16x32_bf16 v[80:83], v[196:199], v[144:147], v[80:83]
	v_mfma_f32_16x16x32_bf16 v[88:91], v[196:199], v[148:151], v[88:91]
	s_waitcnt lgkmcnt(2)
	v_mfma_f32_16x16x32_bf16 v[84:87], v[200:203], v[144:147], v[84:87]
	v_mfma_f32_16x16x32_bf16 v[92:95], v[200:203], v[148:151], v[92:95]
	s_waitcnt lgkmcnt(1)
	v_mfma_f32_16x16x32_bf16 v[64:67], v[204:207], v[144:147], v[64:67]
	v_mfma_f32_16x16x32_bf16 v[72:75], v[204:207], v[148:151], v[72:75]
	s_waitcnt lgkmcnt(0)
	v_mfma_f32_16x16x32_bf16 v[68:71], v[242:245], v[144:147], v[68:71]
	v_mfma_f32_16x16x32_bf16 v[76:79], v[242:245], v[148:151], v[76:79]
	global_load_dwordx4 v[144:147], v[248:249], off
	global_load_dwordx4 v[148:151], v[248:249], off offset:256
	s_waitcnt vmcnt(6)
	s_barrier
	s_add_i32 s3, s3, 6
	s_cmp_lt_u32 s3, 30
	s_cbranch_scc1 .Lg16_outh_k
	s_lshl_b32 s16, s8, 8
	s_lshl_b32 s18, s2, 9
	v_readlane_b32 s12, v254, 38
	v_readlane_b32 s13, v254, 37
	v_readlane_b32 s22, v254, 40
	v_readlane_b32 s23, v254, 39
	s_add_i32 s17, s16, 0xffff8000
	s_cmpk_lt_u32 s8, 0x80
	s_cselect_b32 s12, s12, s22
	s_cselect_b32 s13, s13, s23
	s_cselect_b32 s16, s16, s17
	s_mov_b32 s17, 0
	s_lshl_b64 s[16:17], s[16:17], 12
	s_add_u32 s16, s16, s18
	s_addc_u32 s17, s17, 0
	s_add_u32 s12, s12, s16
	s_addc_u32 s13, s13, s17
	v_lshlrev_b32_e32 v167, 12, v179
	global_load_dword v163, v167, s[12:13]
	global_load_dword v164, v167, s[12:13] offset:128
	global_load_dword v165, v167, s[12:13] offset:256
	global_load_dword v166, v167, s[12:13] offset:384
	ds_read_b128 v[196:199], v246 offset:0
	ds_read_b128 v[200:203], v162 offset:0
	ds_read_b128 v[204:207], v246 offset:2048
	ds_read_b128 v[242:245], v162 offset:2048
	s_waitcnt vmcnt(8) lgkmcnt(3)
	v_mfma_f32_16x16x32_bf16 v[112:115], v[196:199], v[128:131], v[112:115]
	v_mfma_f32_16x16x32_bf16 v[120:123], v[196:199], v[132:135], v[120:123]
	ds_read_b128 v[196:199], v246 offset:4096
	s_waitcnt lgkmcnt(3)
	v_mfma_f32_16x16x32_bf16 v[116:119], v[200:203], v[128:131], v[116:119]
	v_mfma_f32_16x16x32_bf16 v[124:127], v[200:203], v[132:135], v[124:127]
	ds_read_b128 v[200:203], v162 offset:4096
	s_waitcnt lgkmcnt(3)
	v_mfma_f32_16x16x32_bf16 v[96:99], v[204:207], v[128:131], v[96:99]
	v_mfma_f32_16x16x32_bf16 v[104:107], v[204:207], v[132:135], v[104:107]
	ds_read_b128 v[204:207], v246 offset:6144
	s_waitcnt lgkmcnt(3)
	v_mfma_f32_16x16x32_bf16 v[100:103], v[242:245], v[128:131], v[100:103]
	v_mfma_f32_16x16x32_bf16 v[108:111], v[242:245], v[132:135], v[108:111]
	ds_read_b128 v[242:245], v162 offset:6144
	s_waitcnt lgkmcnt(3)
	v_mfma_f32_16x16x32_bf16 v[80:83], v[196:199], v[128:131], v[80:83]
	v_mfma_f32_16x16x32_bf16 v[88:91], v[196:199], v[132:135], v[88:91]
	s_waitcnt lgkmcnt(2)
	v_mfma_f32_16x16x32_bf16 v[84:87], v[200:203], v[128:131], v[84:87]
	v_mfma_f32_16x16x32_bf16 v[92:95], v[200:203], v[132:135], v[92:95]
	s_waitcnt lgkmcnt(1)
	v_mfma_f32_16x16x32_bf16 v[64:67], v[204:207], v[128:131], v[64:67]
	v_mfma_f32_16x16x32_bf16 v[72:75], v[204:207], v[132:135], v[72:75]
	s_waitcnt lgkmcnt(0)
	v_mfma_f32_16x16x32_bf16 v[68:71], v[242:245], v[128:131], v[68:71]
	v_mfma_f32_16x16x32_bf16 v[76:79], v[242:245], v[132:135], v[76:79]
	s_waitcnt vmcnt(6)
	s_barrier
	ds_read_b128 v[196:199], v246 offset:8192
	ds_read_b128 v[200:203], v162 offset:8192
	ds_read_b128 v[204:207], v246 offset:10240
	ds_read_b128 v[242:245], v162 offset:10240
	s_waitcnt vmcnt(4) lgkmcnt(3)
	v_mfma_f32_16x16x32_bf16 v[112:115], v[196:199], v[144:147], v[112:115]
	v_mfma_f32_16x16x32_bf16 v[120:123], v[196:199], v[148:151], v[120:123]
	ds_read_b128 v[196:199], v246 offset:12288
	s_waitcnt lgkmcnt(3)
	v_mfma_f32_16x16x32_bf16 v[116:119], v[200:203], v[144:147], v[116:119]
	v_mfma_f32_16x16x32_bf16 v[124:127], v[200:203], v[148:151], v[124:127]
	ds_read_b128 v[200:203], v162 offset:12288
	s_waitcnt lgkmcnt(3)
	v_mfma_f32_16x16x32_bf16 v[96:99], v[204:207], v[144:147], v[96:99]
	v_mfma_f32_16x16x32_bf16 v[104:107], v[204:207], v[148:151], v[104:107]
	ds_read_b128 v[204:207], v246 offset:14336
	s_waitcnt lgkmcnt(3)
	v_mfma_f32_16x16x32_bf16 v[100:103], v[242:245], v[144:147], v[100:103]
	v_mfma_f32_16x16x32_bf16 v[108:111], v[242:245], v[148:151], v[108:111]
	ds_read_b128 v[242:245], v162 offset:14336
	s_waitcnt lgkmcnt(3)
	v_mfma_f32_16x16x32_bf16 v[80:83], v[196:199], v[144:147], v[80:83]
	v_mfma_f32_16x16x32_bf16 v[88:91], v[196:199], v[148:151], v[88:91]
	s_waitcnt lgkmcnt(2)
	v_mfma_f32_16x16x32_bf16 v[84:87], v[200:203], v[144:147], v[84:87]
	v_mfma_f32_16x16x32_bf16 v[92:95], v[200:203], v[148:151], v[92:95]
	s_waitcnt lgkmcnt(1)
	v_mfma_f32_16x16x32_bf16 v[64:67], v[204:207], v[144:147], v[64:67]
	v_mfma_f32_16x16x32_bf16 v[72:75], v[204:207], v[148:151], v[72:75]
	s_waitcnt lgkmcnt(0)
	v_mfma_f32_16x16x32_bf16 v[68:71], v[242:245], v[144:147], v[68:71]
	v_mfma_f32_16x16x32_bf16 v[76:79], v[242:245], v[148:151], v[76:79]
	s_barrier
	s_nop 7
	s_nop 1
	s_waitcnt vmcnt(0)
	s_waitcnt vmcnt(0)
	v_and_b32_e32 v188, 63, v179
	v_lshrrev_b32_e32 v189, 6, v179
	v_mul_u32_u24_e32 v249, 0x2400, v189
	v_mov_b32_e32 v250, v249
	v_and_b32_e32 v251, 15, v188
	v_mul_u32_u24_e32 v251, 0x110, v251
	v_add_u32_e32 v249, v249, v251
	v_lshrrev_b32_e32 v251, 4, v188
	v_lshl_add_u32 v249, v251, 5, v249
	v_lshrrev_b32_e32 v237, 4, v188
	v_mul_u32_u24_e32 v251, 0x110, v237
	v_add_u32_e32 v250, v250, v251
	v_and_b32_e32 v251, 15, v188
	v_lshlrev_b32_e32 v251, 4, v251
	v_add_u32_e32 v250, v250, v251
	v_lshl_add_u32 v237, v189, 6, v237
	v_lshl_add_u32 v237, v237, 12, v251
	v_add_u32_e32 v238, 16384, v237
	v_add_u32_e32 v239, 32768, v237
	v_add_u32_e32 v240, 49152, v237
	v_add_u32_e32 v241, 65536, v237
	v_add_u32_e32 v242, 81920, v237
	v_add_u32_e32 v243, 98304, v237
	v_add_u32_e32 v248, 114688, v237
	s_lshl_b32 s16, s8, 8
	s_lshl_b32 s18, s2, 9
	s_lshr_b32 s19, s8, 4
	v_readlane_b32 s12, v254, 38
	v_readlane_b32 s13, v254, 37
	v_readlane_b32 s14, v253, 46
	v_readlane_b32 s15, v253, 47
	v_readlane_b32 s22, v254, 40
	v_readlane_b32 s23, v254, 39
	s_add_i32 s17, s16, 0xffff8000
	s_cmpk_lt_u32 s8, 0x80
	s_cselect_b32 s12, s12, s22
	s_cselect_b32 s13, s13, s23
	s_cselect_b32 s14, s14, s62
	s_cselect_b32 s15, s15, s63
	s_cselect_b32 s19, s19, 8
	s_cselect_b32 s16, s16, s17
	s_mov_b32 s17, 0
	s_lshl_b64 s[16:17], s[16:17], 12
	s_add_u32 s16, s16, s18
	s_addc_u32 s17, s17, 0
	s_add_u32 s12, s12, s16
	s_addc_u32 s13, s13, s17
	s_add_u32 s14, s14, s16
	s_addc_u32 s15, s15, s17
	s_mul_i32 s19, s19, 0x6000
	s_add_u32 s20, s0, s19
	s_addc_u32 s21, s1, 0
	s_add_u32 s20, s20, s18
	s_addc_u32 s21, s21, 0
	s_cmp_eq_u32 s101, 1
	s_cbranch_scc0 .Lre_outh_h0
	s_add_u32 s12, s12, 0x20000
	s_addc_u32 s13, s13, 0
	s_add_u32 s14, s14, 0x20000
	s_addc_u32 s15, s15, 0

.Lg16_down_k:
	s_add_i32 s9, s8, 2
	s_lshl_b32 s96, s9, 13
	s_add_i32 m0, vcc_lo, 16384
	v_lshl_add_u64 v[160:161], v[188:189], 0, s[96:97]
	global_load_lds_dwordx4 v[160:161], off
	global_load_lds_dwordx4 v[160:161], off offset:1024
	ds_read_b128 v[196:199], v246 offset:0
	ds_read_b128 v[200:203], v162 offset:0
	ds_read_b128 v[204:207], v246 offset:2048
	ds_read_b128 v[242:245], v162 offset:2048
	s_add_i32 s9, s8, 2
	s_lshl_b32 s96, s9, 11
	v_lshl_add_u64 v[248:249], v[184:185], 0, s[96:97]
	v_lshl_add_u64 v[250:251], v[186:187], 0, s[96:97]
	s_waitcnt vmcnt(8) lgkmcnt(3)
	v_mfma_f32_16x16x32_bf16 v[112:115], v[196:199], v[128:131], v[112:115]
	v_mfma_f32_16x16x32_bf16 v[120:123], v[196:199], v[132:135], v[120:123]
	v_mfma_f32_16x16x32_bf16 v[48:51], v[196:199], v[136:139], v[48:51]
	v_mfma_f32_16x16x32_bf16 v[56:59], v[196:199], v[140:143], v[56:59]
	ds_read_b128 v[196:199], v246 offset:4096
	s_waitcnt lgkmcnt(3)
	v_mfma_f32_16x16x32_bf16 v[116:119], v[200:203], v[128:131], v[116:119]
	v_mfma_f32_16x16x32_bf16 v[124:127], v[200:203], v[132:135], v[124:127]
	v_mfma_f32_16x16x32_bf16 v[52:55], v[200:203], v[136:139], v[52:55]
	v_mfma_f32_16x16x32_bf16 v[60:63], v[200:203], v[140:143], v[60:63]
	ds_read_b128 v[200:203], v162 offset:4096
	s_waitcnt lgkmcnt(3)
	v_mfma_f32_16x16x32_bf16 v[96:99], v[204:207], v[128:131], v[96:99]
	v_mfma_f32_16x16x32_bf16 v[104:107], v[204:207], v[132:135], v[104:107]
	v_mfma_f32_16x16x32_bf16 v[32:35], v[204:207], v[136:139], v[32:35]
	v_mfma_f32_16x16x32_bf16 v[40:43], v[204:207], v[140:143], v[40:43]
	ds_read_b128 v[204:207], v246 offset:6144
	s_waitcnt lgkmcnt(3)
	v_mfma_f32_16x16x32_bf16 v[100:103], v[242:245], v[128:131], v[100:103]
	v_mfma_f32_16x16x32_bf16 v[108:111], v[242:245], v[132:135], v[108:111]
	v_mfma_f32_16x16x32_bf16 v[36:39], v[242:245], v[136:139], v[36:39]
	v_mfma_f32_16x16x32_bf16 v[44:47], v[242:245], v[140:143], v[44:47]
	ds_read_b128 v[242:245], v162 offset:6144
	s_waitcnt lgkmcnt(3)
	v_mfma_f32_16x16x32_bf16 v[80:83], v[196:199], v[128:131], v[80:83]
	v_mfma_f32_16x16x32_bf16 v[88:91], v[196:199], v[132:135], v[88:91]
	v_mfma_f32_16x16x32_bf16 v[16:19], v[196:199], v[136:139], v[16:19]
	v_mfma_f32_16x16x32_bf16 v[24:27], v[196:199], v[140:143], v[24:27]
	s_waitcnt lgkmcnt(2)
	v_mfma_f32_16x16x32_bf16 v[84:87], v[200:203], v[128:131], v[84:87]
	v_mfma_f32_16x16x32_bf16 v[92:95], v[200:203], v[132:135], v[92:95]
	v_mfma_f32_16x16x32_bf16 v[20:23], v[200:203], v[136:139], v[20:23]
	v_mfma_f32_16x16x32_bf16 v[28:31], v[200:203], v[140:143], v[28:31]
	s_waitcnt lgkmcnt(1)
	v_mfma_f32_16x16x32_bf16 v[64:67], v[204:207], v[128:131], v[64:67]
	v_mfma_f32_16x16x32_bf16 v[72:75], v[204:207], v[132:135], v[72:75]
	v_mfma_f32_16x16x32_bf16 v[0:3], v[204:207], v[136:139], v[0:3]
	v_mfma_f32_16x16x32_bf16 v[8:11], v[204:207], v[140:143], v[8:11]
	s_waitcnt lgkmcnt(0)
	v_mfma_f32_16x16x32_bf16 v[68:71], v[242:245], v[128:131], v[68:71]
	v_mfma_f32_16x16x32_bf16 v[76:79], v[242:245], v[132:135], v[76:79]
	v_mfma_f32_16x16x32_bf16 v[4:7], v[242:245], v[136:139], v[4:7]
	v_mfma_f32_16x16x32_bf16 v[12:15], v[242:245], v[140:143], v[12:15]
	global_load_dwordx4 v[128:131], v[248:249], off
	global_load_dwordx4 v[132:135], v[248:249], off offset:256
	global_load_dwordx4 v[136:139], v[250:251], off
	global_load_dwordx4 v[140:143], v[250:251], off offset:256
	s_waitcnt vmcnt(10)
	s_barrier
	s_add_i32 s9, s8, 3
	s_lshl_b32 s96, s9, 13
	s_mov_b32 m0, vcc_lo
	v_lshl_add_u64 v[160:161], v[188:189], 0, s[96:97]
	global_load_lds_dwordx4 v[160:161], off
	global_load_lds_dwordx4 v[160:161], off offset:1024
	ds_read_b128 v[196:199], v246 offset:8192
	ds_read_b128 v[200:203], v162 offset:8192
	ds_read_b128 v[204:207], v246 offset:10240
	ds_read_b128 v[242:245], v162 offset:10240
	s_add_i32 s9, s8, 3
	s_lshl_b32 s96, s9, 11
	v_lshl_add_u64 v[248:249], v[184:185], 0, s[96:97]
	v_lshl_add_u64 v[250:251], v[186:187], 0, s[96:97]
	s_waitcnt vmcnt(8) lgkmcnt(3)
	v_mfma_f32_16x16x32_bf16 v[112:115], v[196:199], v[144:147], v[112:115]
	v_mfma_f32_16x16x32_bf16 v[120:123], v[196:199], v[148:151], v[120:123]
	v_mfma_f32_16x16x32_bf16 v[48:51], v[196:199], v[152:155], v[48:51]
	v_mfma_f32_16x16x32_bf16 v[56:59], v[196:199], v[156:159], v[56:59]
	ds_read_b128 v[196:199], v246 offset:12288
	s_waitcnt lgkmcnt(3)
	v_mfma_f32_16x16x32_bf16 v[116:119], v[200:203], v[144:147], v[116:119]
	v_mfma_f32_16x16x32_bf16 v[124:127], v[200:203], v[148:151], v[124:127]
	v_mfma_f32_16x16x32_bf16 v[52:55], v[200:203], v[152:155], v[52:55]
	v_mfma_f32_16x16x32_bf16 v[60:63], v[200:203], v[156:159], v[60:63]
	ds_read_b128 v[200:203], v162 offset:12288
	s_waitcnt lgkmcnt(3)
	v_mfma_f32_16x16x32_bf16 v[96:99], v[204:207], v[144:147], v[96:99]
	v_mfma_f32_16x16x32_bf16 v[104:107], v[204:207], v[148:151], v[104:107]
	v_mfma_f32_16x16x32_bf16 v[32:35], v[204:207], v[152:155], v[32:35]
	v_mfma_f32_16x16x32_bf16 v[40:43], v[204:207], v[156:159], v[40:43]
	ds_read_b128 v[204:207], v246 offset:14336
	s_waitcnt lgkmcnt(3)
	v_mfma_f32_16x16x32_bf16 v[100:103], v[242:245], v[144:147], v[100:103]
	v_mfma_f32_16x16x32_bf16 v[108:111], v[242:245], v[148:151], v[108:111]
	v_mfma_f32_16x16x32_bf16 v[36:39], v[242:245], v[152:155], v[36:39]
	v_mfma_f32_16x16x32_bf16 v[44:47], v[242:245], v[156:159], v[44:47]
	ds_read_b128 v[242:245], v162 offset:14336
	s_waitcnt lgkmcnt(3)
	v_mfma_f32_16x16x32_bf16 v[80:83], v[196:199], v[144:147], v[80:83]
	v_mfma_f32_16x16x32_bf16 v[88:91], v[196:199], v[148:151], v[88:91]
	v_mfma_f32_16x16x32_bf16 v[16:19], v[196:199], v[152:155], v[16:19]
	v_mfma_f32_16x16x32_bf16 v[24:27], v[196:199], v[156:159], v[24:27]
	s_waitcnt lgkmcnt(2)
	v_mfma_f32_16x16x32_bf16 v[84:87], v[200:203], v[144:147], v[84:87]
	v_mfma_f32_16x16x32_bf16 v[92:95], v[200:203], v[148:151], v[92:95]
	v_mfma_f32_16x16x32_bf16 v[20:23], v[200:203], v[152:155], v[20:23]
	v_mfma_f32_16x16x32_bf16 v[28:31], v[200:203], v[156:159], v[28:31]
	s_waitcnt lgkmcnt(1)
	v_mfma_f32_16x16x32_bf16 v[64:67], v[204:207], v[144:147], v[64:67]
	v_mfma_f32_16x16x32_bf16 v[72:75], v[204:207], v[148:151], v[72:75]
	v_mfma_f32_16x16x32_bf16 v[0:3], v[204:207], v[152:155], v[0:3]
	v_mfma_f32_16x16x32_bf16 v[8:11], v[204:207], v[156:159], v[8:11]
	s_waitcnt lgkmcnt(0)
	v_mfma_f32_16x16x32_bf16 v[68:71], v[242:245], v[144:147], v[68:71]
	v_mfma_f32_16x16x32_bf16 v[76:79], v[242:245], v[148:151], v[76:79]
	v_mfma_f32_16x16x32_bf16 v[4:7], v[242:245], v[152:155], v[4:7]
	v_mfma_f32_16x16x32_bf16 v[12:15], v[242:245], v[156:159], v[12:15]
	global_load_dwordx4 v[144:147], v[248:249], off
	global_load_dwordx4 v[148:151], v[248:249], off offset:256
	global_load_dwordx4 v[152:155], v[250:251], off
	global_load_dwordx4 v[156:159], v[250:251], off offset:256
	s_waitcnt vmcnt(10)
	s_barrier
	s_add_i32 s9, s8, 4
	s_lshl_b32 s96, s9, 13
	s_add_i32 m0, vcc_lo, 8192
	v_lshl_add_u64 v[160:161], v[188:189], 0, s[96:97]
	global_load_lds_dwordx4 v[160:161], off
	global_load_lds_dwordx4 v[160:161], off offset:1024
	ds_read_b128 v[196:199], v246 offset:16384
	ds_read_b128 v[200:203], v162 offset:16384
	ds_read_b128 v[204:207], v246 offset:18432
	ds_read_b128 v[242:245], v162 offset:18432
	s_add_i32 s9, s8, 4
	s_lshl_b32 s96, s9, 11
	v_lshl_add_u64 v[248:249], v[184:185], 0, s[96:97]
	v_lshl_add_u64 v[250:251], v[186:187], 0, s[96:97]
	s_waitcnt vmcnt(8) lgkmcnt(3)
	v_mfma_f32_16x16x32_bf16 v[112:115], v[196:199], v[128:131], v[112:115]
	v_mfma_f32_16x16x32_bf16 v[120:123], v[196:199], v[132:135], v[120:123]
	v_mfma_f32_16x16x32_bf16 v[48:51], v[196:199], v[136:139], v[48:51]
	v_mfma_f32_16x16x32_bf16 v[56:59], v[196:199], v[140:143], v[56:59]
	ds_read_b128 v[196:199], v246 offset:20480
	s_waitcnt lgkmcnt(3)
	v_mfma_f32_16x16x32_bf16 v[116:119], v[200:203], v[128:131], v[116:119]
	v_mfma_f32_16x16x32_bf16 v[124:127], v[200:203], v[132:135], v[124:127]
	v_mfma_f32_16x16x32_bf16 v[52:55], v[200:203], v[136:139], v[52:55]
	v_mfma_f32_16x16x32_bf16 v[60:63], v[200:203], v[140:143], v[60:63]
	ds_read_b128 v[200:203], v162 offset:20480
	s_waitcnt lgkmcnt(3)
	v_mfma_f32_16x16x32_bf16 v[96:99], v[204:207], v[128:131], v[96:99]
	v_mfma_f32_16x16x32_bf16 v[104:107], v[204:207], v[132:135], v[104:107]
	v_mfma_f32_16x16x32_bf16 v[32:35], v[204:207], v[136:139], v[32:35]
	v_mfma_f32_16x16x32_bf16 v[40:43], v[204:207], v[140:143], v[40:43]
	ds_read_b128 v[204:207], v246 offset:22528
	s_waitcnt lgkmcnt(3)
	v_mfma_f32_16x16x32_bf16 v[100:103], v[242:245], v[128:131], v[100:103]
	v_mfma_f32_16x16x32_bf16 v[108:111], v[242:245], v[132:135], v[108:111]
	v_mfma_f32_16x16x32_bf16 v[36:39], v[242:245], v[136:139], v[36:39]
	v_mfma_f32_16x16x32_bf16 v[44:47], v[242:245], v[140:143], v[44:47]
	ds_read_b128 v[242:245], v162 offset:22528
	s_waitcnt lgkmcnt(3)
	v_mfma_f32_16x16x32_bf16 v[80:83], v[196:199], v[128:131], v[80:83]
	v_mfma_f32_16x16x32_bf16 v[88:91], v[196:199], v[132:135], v[88:91]
	v_mfma_f32_16x16x32_bf16 v[16:19], v[196:199], v[136:139], v[16:19]
	v_mfma_f32_16x16x32_bf16 v[24:27], v[196:199], v[140:143], v[24:27]
	s_waitcnt lgkmcnt(2)
	v_mfma_f32_16x16x32_bf16 v[84:87], v[200:203], v[128:131], v[84:87]
	v_mfma_f32_16x16x32_bf16 v[92:95], v[200:203], v[132:135], v[92:95]
	v_mfma_f32_16x16x32_bf16 v[20:23], v[200:203], v[136:139], v[20:23]
	v_mfma_f32_16x16x32_bf16 v[28:31], v[200:203], v[140:143], v[28:31]
	s_waitcnt lgkmcnt(1)
	v_mfma_f32_16x16x32_bf16 v[64:67], v[204:207], v[128:131], v[64:67]
	v_mfma_f32_16x16x32_bf16 v[72:75], v[204:207], v[132:135], v[72:75]
	v_mfma_f32_16x16x32_bf16 v[0:3], v[204:207], v[136:139], v[0:3]
	v_mfma_f32_16x16x32_bf16 v[8:11], v[204:207], v[140:143], v[8:11]
	s_waitcnt lgkmcnt(0)
	v_mfma_f32_16x16x32_bf16 v[68:71], v[242:245], v[128:131], v[68:71]
	v_mfma_f32_16x16x32_bf16 v[76:79], v[242:245], v[132:135], v[76:79]
	v_mfma_f32_16x16x32_bf16 v[4:7], v[242:245], v[136:139], v[4:7]
	v_mfma_f32_16x16x32_bf16 v[12:15], v[242:245], v[140:143], v[12:15]
	global_load_dwordx4 v[128:131], v[248:249], off
	global_load_dwordx4 v[132:135], v[248:249], off offset:256
	global_load_dwordx4 v[136:139], v[250:251], off
	global_load_dwordx4 v[140:143], v[250:251], off offset:256
	s_waitcnt vmcnt(10)
	s_barrier
	s_add_i32 s9, s8, 5
	s_lshl_b32 s96, s9, 13
	s_add_i32 m0, vcc_lo, 16384
	v_lshl_add_u64 v[160:161], v[188:189], 0, s[96:97]
	global_load_lds_dwordx4 v[160:161], off
	global_load_lds_dwordx4 v[160:161], off offset:1024
	ds_read_b128 v[196:199], v246 offset:0
	ds_read_b128 v[200:203], v162 offset:0
	ds_read_b128 v[204:207], v246 offset:2048
	ds_read_b128 v[242:245], v162 offset:2048
	s_add_i32 s9, s8, 5
	s_lshl_b32 s96, s9, 11
	v_lshl_add_u64 v[248:249], v[184:185], 0, s[96:97]
	v_lshl_add_u64 v[250:251], v[186:187], 0, s[96:97]
	s_waitcnt vmcnt(8) lgkmcnt(3)
	v_mfma_f32_16x16x32_bf16 v[112:115], v[196:199], v[144:147], v[112:115]
	v_mfma_f32_16x16x32_bf16 v[120:123], v[196:199], v[148:151], v[120:123]
	v_mfma_f32_16x16x32_bf16 v[48:51], v[196:199], v[152:155], v[48:51]
	v_mfma_f32_16x16x32_bf16 v[56:59], v[196:199], v[156:159], v[56:59]
	ds_read_b128 v[196:199], v246 offset:4096
	s_waitcnt lgkmcnt(3)
	v_mfma_f32_16x16x32_bf16 v[116:119], v[200:203], v[144:147], v[116:119]
	v_mfma_f32_16x16x32_bf16 v[124:127], v[200:203], v[148:151], v[124:127]
	v_mfma_f32_16x16x32_bf16 v[52:55], v[200:203], v[152:155], v[52:55]
	v_mfma_f32_16x16x32_bf16 v[60:63], v[200:203], v[156:159], v[60:63]
	ds_read_b128 v[200:203], v162 offset:4096
	s_waitcnt lgkmcnt(3)
	v_mfma_f32_16x16x32_bf16 v[96:99], v[204:207], v[144:147], v[96:99]
	v_mfma_f32_16x16x32_bf16 v[104:107], v[204:207], v[148:151], v[104:107]
	v_mfma_f32_16x16x32_bf16 v[32:35], v[204:207], v[152:155], v[32:35]
	v_mfma_f32_16x16x32_bf16 v[40:43], v[204:207], v[156:159], v[40:43]
	ds_read_b128 v[204:207], v246 offset:6144
	s_waitcnt lgkmcnt(3)
	v_mfma_f32_16x16x32_bf16 v[100:103], v[242:245], v[144:147], v[100:103]
	v_mfma_f32_16x16x32_bf16 v[108:111], v[242:245], v[148:151], v[108:111]
	v_mfma_f32_16x16x32_bf16 v[36:39], v[242:245], v[152:155], v[36:39]
	v_mfma_f32_16x16x32_bf16 v[44:47], v[242:245], v[156:159], v[44:47]
	ds_read_b128 v[242:245], v162 offset:6144
	s_waitcnt lgkmcnt(3)
	v_mfma_f32_16x16x32_bf16 v[80:83], v[196:199], v[144:147], v[80:83]
	v_mfma_f32_16x16x32_bf16 v[88:91], v[196:199], v[148:151], v[88:91]
	v_mfma_f32_16x16x32_bf16 v[16:19], v[196:199], v[152:155], v[16:19]
	v_mfma_f32_16x16x32_bf16 v[24:27], v[196:199], v[156:159], v[24:27]
	s_waitcnt lgkmcnt(2)
	v_mfma_f32_16x16x32_bf16 v[84:87], v[200:203], v[144:147], v[84:87]
	v_mfma_f32_16x16x32_bf16 v[92:95], v[200:203], v[148:151], v[92:95]
	v_mfma_f32_16x16x32_bf16 v[20:23], v[200:203], v[152:155], v[20:23]
	v_mfma_f32_16x16x32_bf16 v[28:31], v[200:203], v[156:159], v[28:31]
	s_waitcnt lgkmcnt(1)
	v_mfma_f32_16x16x32_bf16 v[64:67], v[204:207], v[144:147], v[64:67]
	v_mfma_f32_16x16x32_bf16 v[72:75], v[204:207], v[148:151], v[72:75]
	v_mfma_f32_16x16x32_bf16 v[0:3], v[204:207], v[152:155], v[0:3]
	v_mfma_f32_16x16x32_bf16 v[8:11], v[204:207], v[156:159], v[8:11]
	s_waitcnt lgkmcnt(0)
	v_mfma_f32_16x16x32_bf16 v[68:71], v[242:245], v[144:147], v[68:71]
	v_mfma_f32_16x16x32_bf16 v[76:79], v[242:245], v[148:151], v[76:79]
	v_mfma_f32_16x16x32_bf16 v[4:7], v[242:245], v[152:155], v[4:7]
	v_mfma_f32_16x16x32_bf16 v[12:15], v[242:245], v[156:159], v[12:15]
	global_load_dwordx4 v[144:147], v[248:249], off
	global_load_dwordx4 v[148:151], v[248:249], off offset:256
	global_load_dwordx4 v[152:155], v[250:251], off
	global_load_dwordx4 v[156:159], v[250:251], off offset:256
	s_waitcnt vmcnt(10)
	s_barrier
	s_add_i32 s9, s8, 6
	s_lshl_b32 s96, s9, 13
	s_mov_b32 m0, vcc_lo
	v_lshl_add_u64 v[160:161], v[188:189], 0, s[96:97]
	global_load_lds_dwordx4 v[160:161], off
	global_load_lds_dwordx4 v[160:161], off offset:1024
	ds_read_b128 v[196:199], v246 offset:8192
	ds_read_b128 v[200:203], v162 offset:8192
	ds_read_b128 v[204:207], v246 offset:10240
	ds_read_b128 v[242:245], v162 offset:10240
	s_add_i32 s9, s8, 6
	s_lshl_b32 s96, s9, 11
	v_lshl_add_u64 v[248:249], v[184:185], 0, s[96:97]
	v_lshl_add_u64 v[250:251], v[186:187], 0, s[96:97]
	s_waitcnt vmcnt(8) lgkmcnt(3)
	v_mfma_f32_16x16x32_bf16 v[112:115], v[196:199], v[128:131], v[112:115]
	v_mfma_f32_16x16x32_bf16 v[120:123], v[196:199], v[132:135], v[120:123]
	v_mfma_f32_16x16x32_bf16 v[48:51], v[196:199], v[136:139], v[48:51]
	v_mfma_f32_16x16x32_bf16 v[56:59], v[196:199], v[140:143], v[56:59]
	ds_read_b128 v[196:199], v246 offset:12288
	s_waitcnt lgkmcnt(3)
	v_mfma_f32_16x16x32_bf16 v[116:119], v[200:203], v[128:131], v[116:119]
	v_mfma_f32_16x16x32_bf16 v[124:127], v[200:203], v[132:135], v[124:127]
	v_mfma_f32_16x16x32_bf16 v[52:55], v[200:203], v[136:139], v[52:55]
	v_mfma_f32_16x16x32_bf16 v[60:63], v[200:203], v[140:143], v[60:63]
	ds_read_b128 v[200:203], v162 offset:12288
	s_waitcnt lgkmcnt(3)
	v_mfma_f32_16x16x32_bf16 v[96:99], v[204:207], v[128:131], v[96:99]
	v_mfma_f32_16x16x32_bf16 v[104:107], v[204:207], v[132:135], v[104:107]
	v_mfma_f32_16x16x32_bf16 v[32:35], v[204:207], v[136:139], v[32:35]
	v_mfma_f32_16x16x32_bf16 v[40:43], v[204:207], v[140:143], v[40:43]
	ds_read_b128 v[204:207], v246 offset:14336
	s_waitcnt lgkmcnt(3)
	v_mfma_f32_16x16x32_bf16 v[100:103], v[242:245], v[128:131], v[100:103]
	v_mfma_f32_16x16x32_bf16 v[108:111], v[242:245], v[132:135], v[108:111]
	v_mfma_f32_16x16x32_bf16 v[36:39], v[242:245], v[136:139], v[36:39]
	v_mfma_f32_16x16x32_bf16 v[44:47], v[242:245], v[140:143], v[44:47]
	ds_read_b128 v[242:245], v162 offset:14336
	s_waitcnt lgkmcnt(3)
	v_mfma_f32_16x16x32_bf16 v[80:83], v[196:199], v[128:131], v[80:83]
	v_mfma_f32_16x16x32_bf16 v[88:91], v[196:199], v[132:135], v[88:91]
	v_mfma_f32_16x16x32_bf16 v[16:19], v[196:199], v[136:139], v[16:19]
	v_mfma_f32_16x16x32_bf16 v[24:27], v[196:199], v[140:143], v[24:27]
	s_waitcnt lgkmcnt(2)
	v_mfma_f32_16x16x32_bf16 v[84:87], v[200:203], v[128:131], v[84:87]
	v_mfma_f32_16x16x32_bf16 v[92:95], v[200:203], v[132:135], v[92:95]
	v_mfma_f32_16x16x32_bf16 v[20:23], v[200:203], v[136:139], v[20:23]
	v_mfma_f32_16x16x32_bf16 v[28:31], v[200:203], v[140:143], v[28:31]
	s_waitcnt lgkmcnt(1)
	v_mfma_f32_16x16x32_bf16 v[64:67], v[204:207], v[128:131], v[64:67]
	v_mfma_f32_16x16x32_bf16 v[72:75], v[204:207], v[132:135], v[72:75]
	v_mfma_f32_16x16x32_bf16 v[0:3], v[204:207], v[136:139], v[0:3]
	v_mfma_f32_16x16x32_bf16 v[8:11], v[204:207], v[140:143], v[8:11]
	s_waitcnt lgkmcnt(0)
	v_mfma_f32_16x16x32_bf16 v[68:71], v[242:245], v[128:131], v[68:71]
	v_mfma_f32_16x16x32_bf16 v[76:79], v[242:245], v[132:135], v[76:79]
	v_mfma_f32_16x16x32_bf16 v[4:7], v[242:245], v[136:139], v[4:7]
	v_mfma_f32_16x16x32_bf16 v[12:15], v[242:245], v[140:143], v[12:15]
	global_load_dwordx4 v[128:131], v[248:249], off
	global_load_dwordx4 v[132:135], v[248:249], off offset:256
	global_load_dwordx4 v[136:139], v[250:251], off
	global_load_dwordx4 v[140:143], v[250:251], off offset:256
	s_waitcnt vmcnt(10)
	s_barrier
	s_add_i32 s9, s8, 7
	s_lshl_b32 s96, s9, 13
	s_add_i32 m0, vcc_lo, 8192
	v_lshl_add_u64 v[160:161], v[188:189], 0, s[96:97]
	global_load_lds_dwordx4 v[160:161], off
	global_load_lds_dwordx4 v[160:161], off offset:1024
	ds_read_b128 v[196:199], v246 offset:16384
	ds_read_b128 v[200:203], v162 offset:16384
	ds_read_b128 v[204:207], v246 offset:18432
	ds_read_b128 v[242:245], v162 offset:18432
	s_add_i32 s9, s8, 7
	s_lshl_b32 s96, s9, 11
	v_lshl_add_u64 v[248:249], v[184:185], 0, s[96:97]
	v_lshl_add_u64 v[250:251], v[186:187], 0, s[96:97]
	s_waitcnt vmcnt(8) lgkmcnt(3)
	v_mfma_f32_16x16x32_bf16 v[112:115], v[196:199], v[144:147], v[112:115]
	v_mfma_f32_16x16x32_bf16 v[120:123], v[196:199], v[148:151], v[120:123]
	v_mfma_f32_16x16x32_bf16 v[48:51], v[196:199], v[152:155], v[48:51]
	v_mfma_f32_16x16x32_bf16 v[56:59], v[196:199], v[156:159], v[56:59]
	ds_read_b128 v[196:199], v246 offset:20480
	s_waitcnt lgkmcnt(3)
	v_mfma_f32_16x16x32_bf16 v[116:119], v[200:203], v[144:147], v[116:119]
	v_mfma_f32_16x16x32_bf16 v[124:127], v[200:203], v[148:151], v[124:127]
	v_mfma_f32_16x16x32_bf16 v[52:55], v[200:203], v[152:155], v[52:55]
	v_mfma_f32_16x16x32_bf16 v[60:63], v[200:203], v[156:159], v[60:63]
	ds_read_b128 v[200:203], v162 offset:20480
	s_waitcnt lgkmcnt(3)
	v_mfma_f32_16x16x32_bf16 v[96:99], v[204:207], v[144:147], v[96:99]
	v_mfma_f32_16x16x32_bf16 v[104:107], v[204:207], v[148:151], v[104:107]
	v_mfma_f32_16x16x32_bf16 v[32:35], v[204:207], v[152:155], v[32:35]
	v_mfma_f32_16x16x32_bf16 v[40:43], v[204:207], v[156:159], v[40:43]
	ds_read_b128 v[204:207], v246 offset:22528
	s_waitcnt lgkmcnt(3)
	v_mfma_f32_16x16x32_bf16 v[100:103], v[242:245], v[144:147], v[100:103]
	v_mfma_f32_16x16x32_bf16 v[108:111], v[242:245], v[148:151], v[108:111]
	v_mfma_f32_16x16x32_bf16 v[36:39], v[242:245], v[152:155], v[36:39]
	v_mfma_f32_16x16x32_bf16 v[44:47], v[242:245], v[156:159], v[44:47]
	ds_read_b128 v[242:245], v162 offset:22528
	s_waitcnt lgkmcnt(3)
	v_mfma_f32_16x16x32_bf16 v[80:83], v[196:199], v[144:147], v[80:83]
	v_mfma_f32_16x16x32_bf16 v[88:91], v[196:199], v[148:151], v[88:91]
	v_mfma_f32_16x16x32_bf16 v[16:19], v[196:199], v[152:155], v[16:19]
	v_mfma_f32_16x16x32_bf16 v[24:27], v[196:199], v[156:159], v[24:27]
	s_waitcnt lgkmcnt(2)
	v_mfma_f32_16x16x32_bf16 v[84:87], v[200:203], v[144:147], v[84:87]
	v_mfma_f32_16x16x32_bf16 v[92:95], v[200:203], v[148:151], v[92:95]
	v_mfma_f32_16x16x32_bf16 v[20:23], v[200:203], v[152:155], v[20:23]
	v_mfma_f32_16x16x32_bf16 v[28:31], v[200:203], v[156:159], v[28:31]
	s_waitcnt lgkmcnt(1)
	v_mfma_f32_16x16x32_bf16 v[64:67], v[204:207], v[144:147], v[64:67]
	v_mfma_f32_16x16x32_bf16 v[72:75], v[204:207], v[148:151], v[72:75]
	v_mfma_f32_16x16x32_bf16 v[0:3], v[204:207], v[152:155], v[0:3]
	v_mfma_f32_16x16x32_bf16 v[8:11], v[204:207], v[156:159], v[8:11]
	s_waitcnt lgkmcnt(0)
	v_mfma_f32_16x16x32_bf16 v[68:71], v[242:245], v[144:147], v[68:71]
	v_mfma_f32_16x16x32_bf16 v[76:79], v[242:245], v[148:151], v[76:79]
	v_mfma_f32_16x16x32_bf16 v[4:7], v[242:245], v[152:155], v[4:7]
	v_mfma_f32_16x16x32_bf16 v[12:15], v[242:245], v[156:159], v[12:15]
	global_load_dwordx4 v[144:147], v[248:249], off
	global_load_dwordx4 v[148:151], v[248:249], off offset:256
	global_load_dwordx4 v[152:155], v[250:251], off
	global_load_dwordx4 v[156:159], v[250:251], off offset:256
	s_waitcnt vmcnt(10)
	s_barrier
	s_add_i32 s8, s8, 6
	s_cmp_lt_u32 s8, 84
	s_cbranch_scc1 .Lg16_down_k
	s_lshl_b32 s16, s7, 8
	s_lshl_b32 s18, s6, 9
	v_readlane_b32 s12, v253, 46
	v_readlane_b32 s13, v253, 47
	s_add_i32 s17, s16, 0xffff8000
	s_cmpk_lt_u32 s7, 0x80
	s_cselect_b32 s12, s12, s62
	s_cselect_b32 s13, s13, s63
	s_cselect_b32 s16, s16, s17
	s_mov_b32 s17, 0
	s_lshl_b64 s[16:17], s[16:17], 12
	s_add_u32 s16, s16, s18
	s_addc_u32 s17, s17, 0
	s_add_u32 s12, s12, s16
	s_addc_u32 s13, s13, s17
	v_lshlrev_b32_e32 v167, 12, v179
	global_load_dword v163, v167, s[12:13]
	global_load_dword v164, v167, s[12:13] offset:128
	global_load_dword v165, v167, s[12:13] offset:256
	global_load_dword v166, v167, s[12:13] offset:384
	s_mov_b32 s96, 0xac000
	s_add_i32 m0, vcc_lo, 16384
	v_lshl_add_u64 v[160:161], v[188:189], 0, s[96:97]
	global_load_lds_dwordx4 v[160:161], off
	global_load_lds_dwordx4 v[160:161], off offset:1024
	ds_read_b128 v[196:199], v246 offset:0
	ds_read_b128 v[200:203], v162 offset:0
	ds_read_b128 v[204:207], v246 offset:2048
	ds_read_b128 v[242:245], v162 offset:2048
	s_mov_b32 s96, 0x2b000
	v_lshl_add_u64 v[248:249], v[184:185], 0, s[96:97]
	v_lshl_add_u64 v[250:251], v[186:187], 0, s[96:97]
	s_waitcnt vmcnt(12) lgkmcnt(3)
	v_mfma_f32_16x16x32_bf16 v[112:115], v[196:199], v[128:131], v[112:115]
	v_mfma_f32_16x16x32_bf16 v[120:123], v[196:199], v[132:135], v[120:123]
	v_mfma_f32_16x16x32_bf16 v[48:51], v[196:199], v[136:139], v[48:51]
	v_mfma_f32_16x16x32_bf16 v[56:59], v[196:199], v[140:143], v[56:59]
	ds_read_b128 v[196:199], v246 offset:4096
	s_waitcnt lgkmcnt(3)
	v_mfma_f32_16x16x32_bf16 v[116:119], v[200:203], v[128:131], v[116:119]
	v_mfma_f32_16x16x32_bf16 v[124:127], v[200:203], v[132:135], v[124:127]
	v_mfma_f32_16x16x32_bf16 v[52:55], v[200:203], v[136:139], v[52:55]
	v_mfma_f32_16x16x32_bf16 v[60:63], v[200:203], v[140:143], v[60:63]
	ds_read_b128 v[200:203], v162 offset:4096
	s_waitcnt lgkmcnt(3)
	v_mfma_f32_16x16x32_bf16 v[96:99], v[204:207], v[128:131], v[96:99]
	v_mfma_f32_16x16x32_bf16 v[104:107], v[204:207], v[132:135], v[104:107]
	v_mfma_f32_16x16x32_bf16 v[32:35], v[204:207], v[136:139], v[32:35]
	v_mfma_f32_16x16x32_bf16 v[40:43], v[204:207], v[140:143], v[40:43]
	ds_read_b128 v[204:207], v246 offset:6144
	s_waitcnt lgkmcnt(3)
	v_mfma_f32_16x16x32_bf16 v[100:103], v[242:245], v[128:131], v[100:103]
	v_mfma_f32_16x16x32_bf16 v[108:111], v[242:245], v[132:135], v[108:111]
	v_mfma_f32_16x16x32_bf16 v[36:39], v[242:245], v[136:139], v[36:39]
	v_mfma_f32_16x16x32_bf16 v[44:47], v[242:245], v[140:143], v[44:47]
	ds_read_b128 v[242:245], v162 offset:6144
	s_waitcnt lgkmcnt(3)
	v_mfma_f32_16x16x32_bf16 v[80:83], v[196:199], v[128:131], v[80:83]
	v_mfma_f32_16x16x32_bf16 v[88:91], v[196:199], v[132:135], v[88:91]
	v_mfma_f32_16x16x32_bf16 v[16:19], v[196:199], v[136:139], v[16:19]
	v_mfma_f32_16x16x32_bf16 v[24:27], v[196:199], v[140:143], v[24:27]
	s_waitcnt lgkmcnt(2)
	v_mfma_f32_16x16x32_bf16 v[84:87], v[200:203], v[128:131], v[84:87]
	v_mfma_f32_16x16x32_bf16 v[92:95], v[200:203], v[132:135], v[92:95]
	v_mfma_f32_16x16x32_bf16 v[20:23], v[200:203], v[136:139], v[20:23]
	v_mfma_f32_16x16x32_bf16 v[28:31], v[200:203], v[140:143], v[28:31]
	s_waitcnt lgkmcnt(1)
	v_mfma_f32_16x16x32_bf16 v[64:67], v[204:207], v[128:131], v[64:67]
	v_mfma_f32_16x16x32_bf16 v[72:75], v[204:207], v[132:135], v[72:75]
	v_mfma_f32_16x16x32_bf16 v[0:3], v[204:207], v[136:139], v[0:3]
	v_mfma_f32_16x16x32_bf16 v[8:11], v[204:207], v[140:143], v[8:11]
	s_waitcnt lgkmcnt(0)
	v_mfma_f32_16x16x32_bf16 v[68:71], v[242:245], v[128:131], v[68:71]
	v_mfma_f32_16x16x32_bf16 v[76:79], v[242:245], v[132:135], v[76:79]
	v_mfma_f32_16x16x32_bf16 v[4:7], v[242:245], v[136:139], v[4:7]
	v_mfma_f32_16x16x32_bf16 v[12:15], v[242:245], v[140:143], v[12:15]
	global_load_dwordx4 v[128:131], v[248:249], off
	global_load_dwordx4 v[132:135], v[248:249], off offset:256
	global_load_dwordx4 v[136:139], v[250:251], off
	global_load_dwordx4 v[140:143], v[250:251], off offset:256
	s_waitcnt vmcnt(14)
	s_barrier
	s_mov_b32 s96, 0xae000
	s_mov_b32 m0, vcc_lo
	v_lshl_add_u64 v[160:161], v[188:189], 0, s[96:97]
	global_load_lds_dwordx4 v[160:161], off
	global_load_lds_dwordx4 v[160:161], off offset:1024
	ds_read_b128 v[196:199], v246 offset:8192
	ds_read_b128 v[200:203], v162 offset:8192
	ds_read_b128 v[204:207], v246 offset:10240
	ds_read_b128 v[242:245], v162 offset:10240
	s_mov_b32 s96, 0x2b800
	v_lshl_add_u64 v[248:249], v[184:185], 0, s[96:97]
	v_lshl_add_u64 v[250:251], v[186:187], 0, s[96:97]
	s_waitcnt vmcnt(12) lgkmcnt(3)
	v_mfma_f32_16x16x32_bf16 v[112:115], v[196:199], v[144:147], v[112:115]
	v_mfma_f32_16x16x32_bf16 v[120:123], v[196:199], v[148:151], v[120:123]
	v_mfma_f32_16x16x32_bf16 v[48:51], v[196:199], v[152:155], v[48:51]
	v_mfma_f32_16x16x32_bf16 v[56:59], v[196:199], v[156:159], v[56:59]
	ds_read_b128 v[196:199], v246 offset:12288
	s_waitcnt lgkmcnt(3)
	v_mfma_f32_16x16x32_bf16 v[116:119], v[200:203], v[144:147], v[116:119]
	v_mfma_f32_16x16x32_bf16 v[124:127], v[200:203], v[148:151], v[124:127]
	v_mfma_f32_16x16x32_bf16 v[52:55], v[200:203], v[152:155], v[52:55]
	v_mfma_f32_16x16x32_bf16 v[60:63], v[200:203], v[156:159], v[60:63]
	ds_read_b128 v[200:203], v162 offset:12288
	s_waitcnt lgkmcnt(3)
	v_mfma_f32_16x16x32_bf16 v[96:99], v[204:207], v[144:147], v[96:99]
	v_mfma_f32_16x16x32_bf16 v[104:107], v[204:207], v[148:151], v[104:107]
	v_mfma_f32_16x16x32_bf16 v[32:35], v[204:207], v[152:155], v[32:35]
	v_mfma_f32_16x16x32_bf16 v[40:43], v[204:207], v[156:159], v[40:43]
	ds_read_b128 v[204:207], v246 offset:14336
	s_waitcnt lgkmcnt(3)
	v_mfma_f32_16x16x32_bf16 v[100:103], v[242:245], v[144:147], v[100:103]
	v_mfma_f32_16x16x32_bf16 v[108:111], v[242:245], v[148:151], v[108:111]
	v_mfma_f32_16x16x32_bf16 v[36:39], v[242:245], v[152:155], v[36:39]
	v_mfma_f32_16x16x32_bf16 v[44:47], v[242:245], v[156:159], v[44:47]
	ds_read_b128 v[242:245], v162 offset:14336
	s_waitcnt lgkmcnt(3)
	v_mfma_f32_16x16x32_bf16 v[80:83], v[196:199], v[144:147], v[80:83]
	v_mfma_f32_16x16x32_bf16 v[88:91], v[196:199], v[148:151], v[88:91]
	v_mfma_f32_16x16x32_bf16 v[16:19], v[196:199], v[152:155], v[16:19]
	v_mfma_f32_16x16x32_bf16 v[24:27], v[196:199], v[156:159], v[24:27]
	s_waitcnt lgkmcnt(2)
	v_mfma_f32_16x16x32_bf16 v[84:87], v[200:203], v[144:147], v[84:87]
	v_mfma_f32_16x16x32_bf16 v[92:95], v[200:203], v[148:151], v[92:95]
	v_mfma_f32_16x16x32_bf16 v[20:23], v[200:203], v[152:155], v[20:23]
	v_mfma_f32_16x16x32_bf16 v[28:31], v[200:203], v[156:159], v[28:31]
	s_waitcnt lgkmcnt(1)
	v_mfma_f32_16x16x32_bf16 v[64:67], v[204:207], v[144:147], v[64:67]
	v_mfma_f32_16x16x32_bf16 v[72:75], v[204:207], v[148:151], v[72:75]
	v_mfma_f32_16x16x32_bf16 v[0:3], v[204:207], v[152:155], v[0:3]
	v_mfma_f32_16x16x32_bf16 v[8:11], v[204:207], v[156:159], v[8:11]
	s_waitcnt lgkmcnt(0)
	v_mfma_f32_16x16x32_bf16 v[68:71], v[242:245], v[144:147], v[68:71]
	v_mfma_f32_16x16x32_bf16 v[76:79], v[242:245], v[148:151], v[76:79]
	v_mfma_f32_16x16x32_bf16 v[4:7], v[242:245], v[152:155], v[4:7]
	v_mfma_f32_16x16x32_bf16 v[12:15], v[242:245], v[156:159], v[12:15]
	global_load_dwordx4 v[144:147], v[248:249], off
	global_load_dwordx4 v[148:151], v[248:249], off offset:256
	global_load_dwordx4 v[152:155], v[250:251], off
	global_load_dwordx4 v[156:159], v[250:251], off offset:256
	s_waitcnt vmcnt(10)
	s_barrier
	ds_read_b128 v[196:199], v246 offset:16384
	ds_read_b128 v[200:203], v162 offset:16384
	ds_read_b128 v[204:207], v246 offset:18432
	ds_read_b128 v[242:245], v162 offset:18432
	s_waitcnt vmcnt(6) lgkmcnt(3)
	v_mfma_f32_16x16x32_bf16 v[112:115], v[196:199], v[128:131], v[112:115]
	v_mfma_f32_16x16x32_bf16 v[120:123], v[196:199], v[132:135], v[120:123]
	v_mfma_f32_16x16x32_bf16 v[48:51], v[196:199], v[136:139], v[48:51]
	v_mfma_f32_16x16x32_bf16 v[56:59], v[196:199], v[140:143], v[56:59]
	ds_read_b128 v[196:199], v246 offset:20480
	s_waitcnt lgkmcnt(3)
	v_mfma_f32_16x16x32_bf16 v[116:119], v[200:203], v[128:131], v[116:119]
	v_mfma_f32_16x16x32_bf16 v[124:127], v[200:203], v[132:135], v[124:127]
	v_mfma_f32_16x16x32_bf16 v[52:55], v[200:203], v[136:139], v[52:55]
	v_mfma_f32_16x16x32_bf16 v[60:63], v[200:203], v[140:143], v[60:63]
	ds_read_b128 v[200:203], v162 offset:20480
	s_waitcnt lgkmcnt(3)
	v_mfma_f32_16x16x32_bf16 v[96:99], v[204:207], v[128:131], v[96:99]
	v_mfma_f32_16x16x32_bf16 v[104:107], v[204:207], v[132:135], v[104:107]
	v_mfma_f32_16x16x32_bf16 v[32:35], v[204:207], v[136:139], v[32:35]
	v_mfma_f32_16x16x32_bf16 v[40:43], v[204:207], v[140:143], v[40:43]
	ds_read_b128 v[204:207], v246 offset:22528
	s_waitcnt lgkmcnt(3)
	v_mfma_f32_16x16x32_bf16 v[100:103], v[242:245], v[128:131], v[100:103]
	v_mfma_f32_16x16x32_bf16 v[108:111], v[242:245], v[132:135], v[108:111]
	v_mfma_f32_16x16x32_bf16 v[36:39], v[242:245], v[136:139], v[36:39]
	v_mfma_f32_16x16x32_bf16 v[44:47], v[242:245], v[140:143], v[44:47]
	ds_read_b128 v[242:245], v162 offset:22528
	s_waitcnt lgkmcnt(3)
	v_mfma_f32_16x16x32_bf16 v[80:83], v[196:199], v[128:131], v[80:83]
	v_mfma_f32_16x16x32_bf16 v[88:91], v[196:199], v[132:135], v[88:91]
	v_mfma_f32_16x16x32_bf16 v[16:19], v[196:199], v[136:139], v[16:19]
	v_mfma_f32_16x16x32_bf16 v[24:27], v[196:199], v[140:143], v[24:27]
	s_waitcnt lgkmcnt(2)
	v_mfma_f32_16x16x32_bf16 v[84:87], v[200:203], v[128:131], v[84:87]
	v_mfma_f32_16x16x32_bf16 v[92:95], v[200:203], v[132:135], v[92:95]
	v_mfma_f32_16x16x32_bf16 v[20:23], v[200:203], v[136:139], v[20:23]
	v_mfma_f32_16x16x32_bf16 v[28:31], v[200:203], v[140:143], v[28:31]
	s_waitcnt lgkmcnt(1)
	v_mfma_f32_16x16x32_bf16 v[64:67], v[204:207], v[128:131], v[64:67]
	v_mfma_f32_16x16x32_bf16 v[72:75], v[204:207], v[132:135], v[72:75]
	v_mfma_f32_16x16x32_bf16 v[0:3], v[204:207], v[136:139], v[0:3]
	v_mfma_f32_16x16x32_bf16 v[8:11], v[204:207], v[140:143], v[8:11]
	s_waitcnt lgkmcnt(0)
	v_mfma_f32_16x16x32_bf16 v[68:71], v[242:245], v[128:131], v[68:71]
	v_mfma_f32_16x16x32_bf16 v[76:79], v[242:245], v[132:135], v[76:79]
	v_mfma_f32_16x16x32_bf16 v[4:7], v[242:245], v[136:139], v[4:7]
	v_mfma_f32_16x16x32_bf16 v[12:15], v[242:245], v[140:143], v[12:15]
	s_waitcnt vmcnt(4)
	s_barrier
	ds_read_b128 v[196:199], v246 offset:0
	ds_read_b128 v[200:203], v162 offset:0
	ds_read_b128 v[204:207], v246 offset:2048
	ds_read_b128 v[242:245], v162 offset:2048
	s_waitcnt vmcnt(0) lgkmcnt(3)
	v_mfma_f32_16x16x32_bf16 v[112:115], v[196:199], v[144:147], v[112:115]
	v_mfma_f32_16x16x32_bf16 v[120:123], v[196:199], v[148:151], v[120:123]
	v_mfma_f32_16x16x32_bf16 v[48:51], v[196:199], v[152:155], v[48:51]
	v_mfma_f32_16x16x32_bf16 v[56:59], v[196:199], v[156:159], v[56:59]
	ds_read_b128 v[196:199], v246 offset:4096
	s_waitcnt lgkmcnt(3)
	v_mfma_f32_16x16x32_bf16 v[116:119], v[200:203], v[144:147], v[116:119]
	v_mfma_f32_16x16x32_bf16 v[124:127], v[200:203], v[148:151], v[124:127]
	v_mfma_f32_16x16x32_bf16 v[52:55], v[200:203], v[152:155], v[52:55]
	v_mfma_f32_16x16x32_bf16 v[60:63], v[200:203], v[156:159], v[60:63]
	ds_read_b128 v[200:203], v162 offset:4096
	s_waitcnt lgkmcnt(3)
	v_mfma_f32_16x16x32_bf16 v[96:99], v[204:207], v[144:147], v[96:99]
	v_mfma_f32_16x16x32_bf16 v[104:107], v[204:207], v[148:151], v[104:107]
	v_mfma_f32_16x16x32_bf16 v[32:35], v[204:207], v[152:155], v[32:35]
	v_mfma_f32_16x16x32_bf16 v[40:43], v[204:207], v[156:159], v[40:43]
	ds_read_b128 v[204:207], v246 offset:6144
	s_waitcnt lgkmcnt(3)
	v_mfma_f32_16x16x32_bf16 v[100:103], v[242:245], v[144:147], v[100:103]
	v_mfma_f32_16x16x32_bf16 v[108:111], v[242:245], v[148:151], v[108:111]
	v_mfma_f32_16x16x32_bf16 v[36:39], v[242:245], v[152:155], v[36:39]
	v_mfma_f32_16x16x32_bf16 v[44:47], v[242:245], v[156:159], v[44:47]
	ds_read_b128 v[242:245], v162 offset:6144
	s_waitcnt lgkmcnt(3)
	v_mfma_f32_16x16x32_bf16 v[80:83], v[196:199], v[144:147], v[80:83]
	v_mfma_f32_16x16x32_bf16 v[88:91], v[196:199], v[148:151], v[88:91]
	v_mfma_f32_16x16x32_bf16 v[16:19], v[196:199], v[152:155], v[16:19]
	v_mfma_f32_16x16x32_bf16 v[24:27], v[196:199], v[156:159], v[24:27]
	s_waitcnt lgkmcnt(2)
	v_mfma_f32_16x16x32_bf16 v[84:87], v[200:203], v[144:147], v[84:87]
	v_mfma_f32_16x16x32_bf16 v[92:95], v[200:203], v[148:151], v[92:95]
	v_mfma_f32_16x16x32_bf16 v[20:23], v[200:203], v[152:155], v[20:23]
	v_mfma_f32_16x16x32_bf16 v[28:31], v[200:203], v[156:159], v[28:31]
	s_waitcnt lgkmcnt(1)
	v_mfma_f32_16x16x32_bf16 v[64:67], v[204:207], v[144:147], v[64:67]
	v_mfma_f32_16x16x32_bf16 v[72:75], v[204:207], v[148:151], v[72:75]
	v_mfma_f32_16x16x32_bf16 v[0:3], v[204:207], v[152:155], v[0:3]
	v_mfma_f32_16x16x32_bf16 v[8:11], v[204:207], v[156:159], v[8:11]
	s_waitcnt lgkmcnt(0)
	v_mfma_f32_16x16x32_bf16 v[68:71], v[242:245], v[144:147], v[68:71]
	v_mfma_f32_16x16x32_bf16 v[76:79], v[242:245], v[148:151], v[76:79]
	v_mfma_f32_16x16x32_bf16 v[4:7], v[242:245], v[152:155], v[4:7]
	v_mfma_f32_16x16x32_bf16 v[12:15], v[242:245], v[156:159], v[12:15]
	s_barrier
	s_nop 7
	s_nop 1
	s_waitcnt vmcnt(0)
	s_waitcnt vmcnt(0)
	v_and_b32_e32 v188, 63, v179
	v_lshrrev_b32_e32 v189, 6, v179
	v_mul_u32_u24_e32 v249, 0x2400, v189
	v_mov_b32_e32 v250, v249
	v_and_b32_e32 v251, 15, v188
	v_mul_u32_u24_e32 v251, 0x110, v251
	v_add_u32_e32 v249, v249, v251
	v_lshrrev_b32_e32 v251, 4, v188
	v_lshl_add_u32 v249, v251, 5, v249
	v_lshrrev_b32_e32 v237, 4, v188
	v_mul_u32_u24_e32 v251, 0x110, v237
	v_add_u32_e32 v250, v250, v251
	v_and_b32_e32 v251, 15, v188
	v_lshlrev_b32_e32 v251, 4, v251
	v_add_u32_e32 v250, v250, v251
	v_lshl_add_u32 v237, v189, 6, v237
	v_lshl_add_u32 v237, v237, 12, v251
	v_add_u32_e32 v238, 16384, v237
	v_add_u32_e32 v239, 32768, v237
	v_add_u32_e32 v240, 49152, v237
	v_add_u32_e32 v241, 65536, v237
	v_add_u32_e32 v242, 81920, v237
	v_add_u32_e32 v243, 98304, v237
	v_add_u32_e32 v248, 114688, v237
	s_lshl_b32 s16, s7, 8
	s_lshl_b32 s18, s6, 9
	s_lshr_b32 s19, s7, 4
	v_readlane_b32 s12, v253, 46
	v_readlane_b32 s13, v253, 47
	v_readlane_b32 s14, v253, 46
	v_readlane_b32 s15, v253, 47
	s_add_i32 s17, s16, 0xffff8000
	s_cmpk_lt_u32 s7, 0x80
	s_cselect_b32 s12, s12, s62
	s_cselect_b32 s13, s13, s63
	s_cselect_b32 s14, s14, s62
	s_cselect_b32 s15, s15, s63
	s_cselect_b32 s19, s19, 8
	s_cselect_b32 s16, s16, s17
	s_mov_b32 s17, 0
	s_lshl_b64 s[16:17], s[16:17], 12
	s_add_u32 s16, s16, s18
	s_addc_u32 s17, s17, 0
	s_add_u32 s12, s12, s16
	s_addc_u32 s13, s13, s17
	s_add_u32 s14, s14, s16
	s_addc_u32 s15, s15, s17
	s_mul_i32 s19, s19, 0x6000
	s_add_u32 s20, s0, s19
	s_addc_u32 s21, s1, 0
	s_add_u32 s20, s20, s18
	s_addc_u32 s21, s21, 0
	global_load_dwordx4 v[244:247], v251, s[20:21]
	global_load_dwordx4 v[160:163], v237, s[12:13]
	global_load_dwordx4 v[164:167], v238, s[12:13]
	global_load_dwordx4 v[168:171], v239, s[12:13]
	global_load_dwordx4 v[172:175], v240, s[12:13]
	global_load_dwordx4 v[196:199], v241, s[12:13]
	global_load_dwordx4 v[200:203], v242, s[12:13]
	global_load_dwordx4 v[204:207], v243, s[12:13]
	global_load_dwordx4 v[184:187], v248, s[12:13]
	ds_write_b128 v249, v[112:115]
	ds_write_b128 v249, v[116:119] offset:16
	ds_write_b128 v249, v[96:99] offset:128
	ds_write_b128 v249, v[100:103] offset:144
	ds_write_b128 v249, v[120:123] offset:4352
	ds_write_b128 v249, v[124:127] offset:4368
	ds_write_b128 v249, v[104:107] offset:4480
	ds_write_b128 v249, v[108:111] offset:4496
	s_waitcnt lgkmcnt(0)
	ds_read_b128 v[128:131], v250
	ds_read_b128 v[132:135], v250 offset:1088
	ds_read_b128 v[136:139], v250 offset:2176
	ds_read_b128 v[140:143], v250 offset:3264
	ds_read_b128 v[144:147], v250 offset:4352
	ds_read_b128 v[148:151], v250 offset:5440
	ds_read_b128 v[152:155], v250 offset:6528
	ds_read_b128 v[156:159], v250 offset:7616
	s_waitcnt vmcnt(7) lgkmcnt(7)
	v_fma_f32 v128, v244, v128, v160
	v_fma_f32 v129, v245, v129, v161
	v_fma_f32 v130, v246, v130, v162
	v_fma_f32 v131, v247, v131, v163
	global_store_dwordx4 v237, v[128:131], s[14:15] sc0 sc1
	s_waitcnt vmcnt(7) lgkmcnt(6)
	v_fma_f32 v132, v244, v132, v164
	v_fma_f32 v133, v245, v133, v165
	v_fma_f32 v134, v246, v134, v166
	v_fma_f32 v135, v247, v135, v167
	global_store_dwordx4 v238, v[132:135], s[14:15] sc0 sc1
	s_waitcnt vmcnt(7) lgkmcnt(5)
	v_fma_f32 v136, v244, v136, v168
	v_fma_f32 v137, v245, v137, v169
	v_fma_f32 v138, v246, v138, v170
	v_fma_f32 v139, v247, v139, v171
	global_store_dwordx4 v239, v[136:139], s[14:15] sc0 sc1
	s_waitcnt vmcnt(7) lgkmcnt(4)
	v_fma_f32 v140, v244, v140, v172
	v_fma_f32 v141, v245, v141, v173
	v_fma_f32 v142, v246, v142, v174
	v_fma_f32 v143, v247, v143, v175
	global_store_dwordx4 v240, v[140:143], s[14:15] sc0 sc1
	s_waitcnt vmcnt(7) lgkmcnt(3)
	v_fma_f32 v144, v244, v144, v196
	v_fma_f32 v145, v245, v145, v197
	v_fma_f32 v146, v246, v146, v198
	v_fma_f32 v147, v247, v147, v199
	global_store_dwordx4 v241, v[144:147], s[14:15] sc0 sc1
	s_waitcnt vmcnt(7) lgkmcnt(2)
	v_fma_f32 v148, v244, v148, v200
	v_fma_f32 v149, v245, v149, v201
	v_fma_f32 v150, v246, v150, v202
	v_fma_f32 v151, v247, v151, v203
	global_store_dwordx4 v242, v[148:151], s[14:15] sc0 sc1
	s_waitcnt vmcnt(7) lgkmcnt(1)
	v_fma_f32 v152, v244, v152, v204
	v_fma_f32 v153, v245, v153, v205
	v_fma_f32 v154, v246, v154, v206
	v_fma_f32 v155, v247, v155, v207
	global_store_dwordx4 v243, v[152:155], s[14:15] sc0 sc1
	s_waitcnt vmcnt(7) lgkmcnt(0)
	v_fma_f32 v156, v244, v156, v184
	v_fma_f32 v157, v245, v157, v185
	v_fma_f32 v158, v246, v158, v186
	v_fma_f32 v159, v247, v159, v187
	global_store_dwordx4 v248, v[156:159], s[14:15] sc0 sc1
	global_load_dwordx4 v[244:247], v251, s[20:21] offset:256
	global_load_dwordx4 v[160:163], v237, s[12:13] offset:256
	global_load_dwordx4 v[164:167], v238, s[12:13] offset:256
	global_load_dwordx4 v[168:171], v239, s[12:13] offset:256
	global_load_dwordx4 v[172:175], v240, s[12:13] offset:256
	global_load_dwordx4 v[196:199], v241, s[12:13] offset:256
	global_load_dwordx4 v[200:203], v242, s[12:13] offset:256
	global_load_dwordx4 v[204:207], v243, s[12:13] offset:256
	global_load_dwordx4 v[184:187], v248, s[12:13] offset:256
	ds_write_b128 v249, v[80:83]
	ds_write_b128 v249, v[84:87] offset:16
	ds_write_b128 v249, v[64:67] offset:128
	ds_write_b128 v249, v[68:71] offset:144
	ds_write_b128 v249, v[88:91] offset:4352
	ds_write_b128 v249, v[92:95] offset:4368
	ds_write_b128 v249, v[72:75] offset:4480
	ds_write_b128 v249, v[76:79] offset:4496
	s_waitcnt lgkmcnt(0)
	ds_read_b128 v[128:131], v250
	ds_read_b128 v[132:135], v250 offset:1088
	ds_read_b128 v[136:139], v250 offset:2176
	ds_read_b128 v[140:143], v250 offset:3264
	ds_read_b128 v[144:147], v250 offset:4352
	ds_read_b128 v[148:151], v250 offset:5440
	ds_read_b128 v[152:155], v250 offset:6528
	ds_read_b128 v[156:159], v250 offset:7616
	s_waitcnt vmcnt(7) lgkmcnt(7)
	v_fma_f32 v128, v244, v128, v160
	v_fma_f32 v129, v245, v129, v161
	v_fma_f32 v130, v246, v130, v162
	v_fma_f32 v131, v247, v131, v163
	global_store_dwordx4 v237, v[128:131], s[14:15] offset:256 sc0 sc1
	s_waitcnt vmcnt(7) lgkmcnt(6)
	v_fma_f32 v132, v244, v132, v164
	v_fma_f32 v133, v245, v133, v165
	v_fma_f32 v134, v246, v134, v166
	v_fma_f32 v135, v247, v135, v167
	global_store_dwordx4 v238, v[132:135], s[14:15] offset:256 sc0 sc1
	s_waitcnt vmcnt(7) lgkmcnt(5)
	v_fma_f32 v136, v244, v136, v168
	v_fma_f32 v137, v245, v137, v169
	v_fma_f32 v138, v246, v138, v170
	v_fma_f32 v139, v247, v139, v171
	global_store_dwordx4 v239, v[136:139], s[14:15] offset:256 sc0 sc1
	s_waitcnt vmcnt(7) lgkmcnt(4)
	v_fma_f32 v140, v244, v140, v172
	v_fma_f32 v141, v245, v141, v173
	v_fma_f32 v142, v246, v142, v174
	v_fma_f32 v143, v247, v143, v175
	global_store_dwordx4 v240, v[140:143], s[14:15] offset:256 sc0 sc1
	s_waitcnt vmcnt(7) lgkmcnt(3)
	v_fma_f32 v144, v244, v144, v196
	v_fma_f32 v145, v245, v145, v197
	v_fma_f32 v146, v246, v146, v198
	v_fma_f32 v147, v247, v147, v199
	global_store_dwordx4 v241, v[144:147], s[14:15] offset:256 sc0 sc1
	s_waitcnt vmcnt(7) lgkmcnt(2)
	v_fma_f32 v148, v244, v148, v200
	v_fma_f32 v149, v245, v149, v201
	v_fma_f32 v150, v246, v150, v202
	v_fma_f32 v151, v247, v151, v203
	global_store_dwordx4 v242, v[148:151], s[14:15] offset:256 sc0 sc1
	s_waitcnt vmcnt(7) lgkmcnt(1)
	v_fma_f32 v152, v244, v152, v204
	v_fma_f32 v153, v245, v153, v205
	v_fma_f32 v154, v246, v154, v206
	v_fma_f32 v155, v247, v155, v207
	global_store_dwordx4 v243, v[152:155], s[14:15] offset:256 sc0 sc1
	s_waitcnt vmcnt(7) lgkmcnt(0)
	v_fma_f32 v156, v244, v156, v184
	v_fma_f32 v157, v245, v157, v185
	v_fma_f32 v158, v246, v158, v186
	v_fma_f32 v159, v247, v159, v187
	global_store_dwordx4 v248, v[156:159], s[14:15] offset:256 sc0 sc1
	s_add_u32 s12, s12, 0x20000
	s_addc_u32 s13, s13, 0
	s_add_u32 s14, s14, 0x20000
	s_addc_u32 s15, s15, 0
	global_load_dwordx4 v[244:247], v251, s[20:21]
	global_load_dwordx4 v[160:163], v237, s[12:13]
	global_load_dwordx4 v[164:167], v238, s[12:13]
	global_load_dwordx4 v[168:171], v239, s[12:13]
	global_load_dwordx4 v[172:175], v240, s[12:13]
	global_load_dwordx4 v[196:199], v241, s[12:13]
	global_load_dwordx4 v[200:203], v242, s[12:13]
	global_load_dwordx4 v[204:207], v243, s[12:13]
	global_load_dwordx4 v[184:187], v248, s[12:13]
	ds_write_b128 v249, v[48:51]
	ds_write_b128 v249, v[52:55] offset:16
	ds_write_b128 v249, v[32:35] offset:128
	ds_write_b128 v249, v[36:39] offset:144
	ds_write_b128 v249, v[56:59] offset:4352
	ds_write_b128 v249, v[60:63] offset:4368
	ds_write_b128 v249, v[40:43] offset:4480
	ds_write_b128 v249, v[44:47] offset:4496
	s_waitcnt lgkmcnt(0)
	ds_read_b128 v[128:131], v250
	ds_read_b128 v[132:135], v250 offset:1088
	ds_read_b128 v[136:139], v250 offset:2176
	ds_read_b128 v[140:143], v250 offset:3264
	ds_read_b128 v[144:147], v250 offset:4352
	ds_read_b128 v[148:151], v250 offset:5440
	ds_read_b128 v[152:155], v250 offset:6528
	ds_read_b128 v[156:159], v250 offset:7616
	s_waitcnt vmcnt(7) lgkmcnt(7)
	v_fma_f32 v128, v244, v128, v160
	v_fma_f32 v129, v245, v129, v161
	v_fma_f32 v130, v246, v130, v162
	v_fma_f32 v131, v247, v131, v163
	global_store_dwordx4 v237, v[128:131], s[14:15] sc0 sc1
	s_waitcnt vmcnt(7) lgkmcnt(6)
	v_fma_f32 v132, v244, v132, v164
	v_fma_f32 v133, v245, v133, v165
	v_fma_f32 v134, v246, v134, v166
	v_fma_f32 v135, v247, v135, v167
	global_store_dwordx4 v238, v[132:135], s[14:15] sc0 sc1
	s_waitcnt vmcnt(7) lgkmcnt(5)
	v_fma_f32 v136, v244, v136, v168
	v_fma_f32 v137, v245, v137, v169
	v_fma_f32 v138, v246, v138, v170
	v_fma_f32 v139, v247, v139, v171
	global_store_dwordx4 v239, v[136:139], s[14:15] sc0 sc1
	s_waitcnt vmcnt(7) lgkmcnt(4)
	v_fma_f32 v140, v244, v140, v172
	v_fma_f32 v141, v245, v141, v173
	v_fma_f32 v142, v246, v142, v174
	v_fma_f32 v143, v247, v143, v175
	global_store_dwordx4 v240, v[140:143], s[14:15] sc0 sc1
	s_waitcnt vmcnt(7) lgkmcnt(3)
	v_fma_f32 v144, v244, v144, v196
	v_fma_f32 v145, v245, v145, v197
	v_fma_f32 v146, v246, v146, v198
	v_fma_f32 v147, v247, v147, v199
	global_store_dwordx4 v241, v[144:147], s[14:15] sc0 sc1
	s_waitcnt vmcnt(7) lgkmcnt(2)
	v_fma_f32 v148, v244, v148, v200
	v_fma_f32 v149, v245, v149, v201
	v_fma_f32 v150, v246, v150, v202
	v_fma_f32 v151, v247, v151, v203
	global_store_dwordx4 v242, v[148:151], s[14:15] sc0 sc1
	s_waitcnt vmcnt(7) lgkmcnt(1)
	v_fma_f32 v152, v244, v152, v204
	v_fma_f32 v153, v245, v153, v205
	v_fma_f32 v154, v246, v154, v206
	v_fma_f32 v155, v247, v155, v207
	global_store_dwordx4 v243, v[152:155], s[14:15] sc0 sc1
	s_waitcnt vmcnt(7) lgkmcnt(0)
	v_fma_f32 v156, v244, v156, v184
	v_fma_f32 v157, v245, v157, v185
	v_fma_f32 v158, v246, v158, v186
	v_fma_f32 v159, v247, v159, v187
	global_store_dwordx4 v248, v[156:159], s[14:15] sc0 sc1
	global_load_dwordx4 v[244:247], v251, s[20:21] offset:256
	global_load_dwordx4 v[160:163], v237, s[12:13] offset:256
	global_load_dwordx4 v[164:167], v238, s[12:13] offset:256
	global_load_dwordx4 v[168:171], v239, s[12:13] offset:256
	global_load_dwordx4 v[172:175], v240, s[12:13] offset:256
	global_load_dwordx4 v[196:199], v241, s[12:13] offset:256
	global_load_dwordx4 v[200:203], v242, s[12:13] offset:256
	global_load_dwordx4 v[204:207], v243, s[12:13] offset:256
	global_load_dwordx4 v[184:187], v248, s[12:13] offset:256
	ds_write_b128 v249, v[16:19]
	ds_write_b128 v249, v[20:23] offset:16
	ds_write_b128 v249, v[0:3] offset:128
	ds_write_b128 v249, v[4:7] offset:144
	ds_write_b128 v249, v[24:27] offset:4352
	ds_write_b128 v249, v[28:31] offset:4368
	ds_write_b128 v249, v[8:11] offset:4480
	ds_write_b128 v249, v[12:15] offset:4496
	s_waitcnt lgkmcnt(0)
	ds_read_b128 v[128:131], v250
	ds_read_b128 v[132:135], v250 offset:1088
	ds_read_b128 v[136:139], v250 offset:2176
	ds_read_b128 v[140:143], v250 offset:3264
	ds_read_b128 v[144:147], v250 offset:4352
	ds_read_b128 v[148:151], v250 offset:5440
	ds_read_b128 v[152:155], v250 offset:6528
	ds_read_b128 v[156:159], v250 offset:7616
	s_waitcnt vmcnt(7) lgkmcnt(7)
	v_fma_f32 v128, v244, v128, v160
	v_fma_f32 v129, v245, v129, v161
	v_fma_f32 v130, v246, v130, v162
	v_fma_f32 v131, v247, v131, v163
	global_store_dwordx4 v237, v[128:131], s[14:15] offset:256 sc0 sc1
	s_waitcnt vmcnt(7) lgkmcnt(6)
	v_fma_f32 v132, v244, v132, v164
	v_fma_f32 v133, v245, v133, v165
	v_fma_f32 v134, v246, v134, v166
	v_fma_f32 v135, v247, v135, v167
	global_store_dwordx4 v238, v[132:135], s[14:15] offset:256 sc0 sc1
	s_waitcnt vmcnt(7) lgkmcnt(5)
	v_fma_f32 v136, v244, v136, v168
	v_fma_f32 v137, v245, v137, v169
	v_fma_f32 v138, v246, v138, v170
	v_fma_f32 v139, v247, v139, v171
	global_store_dwordx4 v239, v[136:139], s[14:15] offset:256 sc0 sc1
	s_waitcnt vmcnt(7) lgkmcnt(4)
	v_fma_f32 v140, v244, v140, v172
	v_fma_f32 v141, v245, v141, v173
	v_fma_f32 v142, v246, v142, v174
	v_fma_f32 v143, v247, v143, v175
	global_store_dwordx4 v240, v[140:143], s[14:15] offset:256 sc0 sc1
	s_waitcnt vmcnt(7) lgkmcnt(3)
	v_fma_f32 v144, v244, v144, v196
	v_fma_f32 v145, v245, v145, v197
	v_fma_f32 v146, v246, v146, v198
	v_fma_f32 v147, v247, v147, v199
	global_store_dwordx4 v241, v[144:147], s[14:15] offset:256 sc0 sc1
	s_waitcnt vmcnt(7) lgkmcnt(2)
	v_fma_f32 v148, v244, v148, v200
	v_fma_f32 v149, v245, v149, v201
	v_fma_f32 v150, v246, v150, v202
	v_fma_f32 v151, v247, v151, v203
	global_store_dwordx4 v242, v[148:151], s[14:15] offset:256 sc0 sc1
	s_waitcnt vmcnt(7) lgkmcnt(1)
	v_fma_f32 v152, v244, v152, v204
	v_fma_f32 v153, v245, v153, v205
	v_fma_f32 v154, v246, v154, v206
	v_fma_f32 v155, v247, v155, v207
	global_store_dwordx4 v243, v[152:155], s[14:15] offset:256 sc0 sc1
	s_waitcnt vmcnt(7) lgkmcnt(0)
	v_fma_f32 v156, v244, v156, v184
	v_fma_f32 v157, v245, v157, v185
	v_fma_f32 v158, v246, v158, v186
	v_fma_f32 v159, v247, v159, v187
	global_store_dwordx4 v248, v[156:159], s[14:15] offset:256 sc0 sc1
	s_waitcnt lgkmcnt(0)
	v_readlane_b32 s16, v254, 11
	s_andn2_b32 s17, s26, 63
	s_add_i32 s2, s2, s16
	s_cmp_lt_i32 s2, s17
	s_cbranch_scc0 .Lhx_down_left
	s_barrier
	s_branch .LBB0_1086

.Lg16_downh_k:
	s_add_i32 s9, s8, 2
	s_lshl_b32 s96, s9, 13
	s_add_i32 m0, vcc_lo, 16384
	v_lshl_add_u64 v[160:161], v[188:189], 0, s[96:97]
	global_load_lds_dwordx4 v[160:161], off
	global_load_lds_dwordx4 v[160:161], off offset:1024
	ds_read_b128 v[196:199], v246 offset:0
	ds_read_b128 v[200:203], v162 offset:0
	ds_read_b128 v[204:207], v246 offset:2048
	ds_read_b128 v[242:245], v162 offset:2048
	s_add_i32 s9, s8, 2
	s_lshl_b32 s96, s9, 11
	v_lshl_add_u64 v[248:249], v[184:185], 0, s[96:97]
	v_lshl_add_u64 v[250:251], v[186:187], 0, s[96:97]
	s_waitcnt vmcnt(6) lgkmcnt(3)
	v_mfma_f32_16x16x32_bf16 v[112:115], v[196:199], v[128:131], v[112:115]
	v_mfma_f32_16x16x32_bf16 v[120:123], v[196:199], v[132:135], v[120:123]
	ds_read_b128 v[196:199], v246 offset:4096
	s_waitcnt lgkmcnt(3)
	v_mfma_f32_16x16x32_bf16 v[116:119], v[200:203], v[128:131], v[116:119]
	v_mfma_f32_16x16x32_bf16 v[124:127], v[200:203], v[132:135], v[124:127]
	ds_read_b128 v[200:203], v162 offset:4096
	s_waitcnt lgkmcnt(3)
	v_mfma_f32_16x16x32_bf16 v[96:99], v[204:207], v[128:131], v[96:99]
	v_mfma_f32_16x16x32_bf16 v[104:107], v[204:207], v[132:135], v[104:107]
	ds_read_b128 v[204:207], v246 offset:6144
	s_waitcnt lgkmcnt(3)
	v_mfma_f32_16x16x32_bf16 v[100:103], v[242:245], v[128:131], v[100:103]
	v_mfma_f32_16x16x32_bf16 v[108:111], v[242:245], v[132:135], v[108:111]
	ds_read_b128 v[242:245], v162 offset:6144
	s_waitcnt lgkmcnt(3)
	v_mfma_f32_16x16x32_bf16 v[80:83], v[196:199], v[128:131], v[80:83]
	v_mfma_f32_16x16x32_bf16 v[88:91], v[196:199], v[132:135], v[88:91]
	s_waitcnt lgkmcnt(2)
	v_mfma_f32_16x16x32_bf16 v[84:87], v[200:203], v[128:131], v[84:87]
	v_mfma_f32_16x16x32_bf16 v[92:95], v[200:203], v[132:135], v[92:95]
	s_waitcnt lgkmcnt(1)
	v_mfma_f32_16x16x32_bf16 v[64:67], v[204:207], v[128:131], v[64:67]
	v_mfma_f32_16x16x32_bf16 v[72:75], v[204:207], v[132:135], v[72:75]
	s_waitcnt lgkmcnt(0)
	v_mfma_f32_16x16x32_bf16 v[68:71], v[242:245], v[128:131], v[68:71]
	v_mfma_f32_16x16x32_bf16 v[76:79], v[242:245], v[132:135], v[76:79]
	global_load_dwordx4 v[128:131], v[248:249], off
	global_load_dwordx4 v[132:135], v[248:249], off offset:256
	s_waitcnt vmcnt(6)
	s_barrier
	s_add_i32 s9, s8, 3
	s_lshl_b32 s96, s9, 13
	s_mov_b32 m0, vcc_lo
	v_lshl_add_u64 v[160:161], v[188:189], 0, s[96:97]
	global_load_lds_dwordx4 v[160:161], off
	global_load_lds_dwordx4 v[160:161], off offset:1024
	ds_read_b128 v[196:199], v246 offset:8192
	ds_read_b128 v[200:203], v162 offset:8192
	ds_read_b128 v[204:207], v246 offset:10240
	ds_read_b128 v[242:245], v162 offset:10240
	s_add_i32 s9, s8, 3
	s_lshl_b32 s96, s9, 11
	v_lshl_add_u64 v[248:249], v[184:185], 0, s[96:97]
	v_lshl_add_u64 v[250:251], v[186:187], 0, s[96:97]
	s_waitcnt vmcnt(6) lgkmcnt(3)
	v_mfma_f32_16x16x32_bf16 v[112:115], v[196:199], v[144:147], v[112:115]
	v_mfma_f32_16x16x32_bf16 v[120:123], v[196:199], v[148:151], v[120:123]
	ds_read_b128 v[196:199], v246 offset:12288
	s_waitcnt lgkmcnt(3)
	v_mfma_f32_16x16x32_bf16 v[116:119], v[200:203], v[144:147], v[116:119]
	v_mfma_f32_16x16x32_bf16 v[124:127], v[200:203], v[148:151], v[124:127]
	ds_read_b128 v[200:203], v162 offset:12288
	s_waitcnt lgkmcnt(3)
	v_mfma_f32_16x16x32_bf16 v[96:99], v[204:207], v[144:147], v[96:99]
	v_mfma_f32_16x16x32_bf16 v[104:107], v[204:207], v[148:151], v[104:107]
	ds_read_b128 v[204:207], v246 offset:14336
	s_waitcnt lgkmcnt(3)
	v_mfma_f32_16x16x32_bf16 v[100:103], v[242:245], v[144:147], v[100:103]
	v_mfma_f32_16x16x32_bf16 v[108:111], v[242:245], v[148:151], v[108:111]
	ds_read_b128 v[242:245], v162 offset:14336
	s_waitcnt lgkmcnt(3)
	v_mfma_f32_16x16x32_bf16 v[80:83], v[196:199], v[144:147], v[80:83]
	v_mfma_f32_16x16x32_bf16 v[88:91], v[196:199], v[148:151], v[88:91]
	s_waitcnt lgkmcnt(2)
	v_mfma_f32_16x16x32_bf16 v[84:87], v[200:203], v[144:147], v[84:87]
	v_mfma_f32_16x16x32_bf16 v[92:95], v[200:203], v[148:151], v[92:95]
	s_waitcnt lgkmcnt(1)
	v_mfma_f32_16x16x32_bf16 v[64:67], v[204:207], v[144:147], v[64:67]
	v_mfma_f32_16x16x32_bf16 v[72:75], v[204:207], v[148:151], v[72:75]
	s_waitcnt lgkmcnt(0)
	v_mfma_f32_16x16x32_bf16 v[68:71], v[242:245], v[144:147], v[68:71]
	v_mfma_f32_16x16x32_bf16 v[76:79], v[242:245], v[148:151], v[76:79]
	global_load_dwordx4 v[144:147], v[248:249], off
	global_load_dwordx4 v[148:151], v[248:249], off offset:256
	s_waitcnt vmcnt(6)
	s_barrier
	s_add_i32 s9, s8, 4
	s_lshl_b32 s96, s9, 13
	s_add_i32 m0, vcc_lo, 8192
	v_lshl_add_u64 v[160:161], v[188:189], 0, s[96:97]
	global_load_lds_dwordx4 v[160:161], off
	global_load_lds_dwordx4 v[160:161], off offset:1024
	ds_read_b128 v[196:199], v246 offset:16384
	ds_read_b128 v[200:203], v162 offset:16384
	ds_read_b128 v[204:207], v246 offset:18432
	ds_read_b128 v[242:245], v162 offset:18432
	s_add_i32 s9, s8, 4
	s_lshl_b32 s96, s9, 11
	v_lshl_add_u64 v[248:249], v[184:185], 0, s[96:97]
	v_lshl_add_u64 v[250:251], v[186:187], 0, s[96:97]
	s_waitcnt vmcnt(6) lgkmcnt(3)
	v_mfma_f32_16x16x32_bf16 v[112:115], v[196:199], v[128:131], v[112:115]
	v_mfma_f32_16x16x32_bf16 v[120:123], v[196:199], v[132:135], v[120:123]
	ds_read_b128 v[196:199], v246 offset:20480
	s_waitcnt lgkmcnt(3)
	v_mfma_f32_16x16x32_bf16 v[116:119], v[200:203], v[128:131], v[116:119]
	v_mfma_f32_16x16x32_bf16 v[124:127], v[200:203], v[132:135], v[124:127]
	ds_read_b128 v[200:203], v162 offset:20480
	s_waitcnt lgkmcnt(3)
	v_mfma_f32_16x16x32_bf16 v[96:99], v[204:207], v[128:131], v[96:99]
	v_mfma_f32_16x16x32_bf16 v[104:107], v[204:207], v[132:135], v[104:107]
	ds_read_b128 v[204:207], v246 offset:22528
	s_waitcnt lgkmcnt(3)
	v_mfma_f32_16x16x32_bf16 v[100:103], v[242:245], v[128:131], v[100:103]
	v_mfma_f32_16x16x32_bf16 v[108:111], v[242:245], v[132:135], v[108:111]
	ds_read_b128 v[242:245], v162 offset:22528
	s_waitcnt lgkmcnt(3)
	v_mfma_f32_16x16x32_bf16 v[80:83], v[196:199], v[128:131], v[80:83]
	v_mfma_f32_16x16x32_bf16 v[88:91], v[196:199], v[132:135], v[88:91]
	s_waitcnt lgkmcnt(2)
	v_mfma_f32_16x16x32_bf16 v[84:87], v[200:203], v[128:131], v[84:87]
	v_mfma_f32_16x16x32_bf16 v[92:95], v[200:203], v[132:135], v[92:95]
	s_waitcnt lgkmcnt(1)
	v_mfma_f32_16x16x32_bf16 v[64:67], v[204:207], v[128:131], v[64:67]
	v_mfma_f32_16x16x32_bf16 v[72:75], v[204:207], v[132:135], v[72:75]
	s_waitcnt lgkmcnt(0)
	v_mfma_f32_16x16x32_bf16 v[68:71], v[242:245], v[128:131], v[68:71]
	v_mfma_f32_16x16x32_bf16 v[76:79], v[242:245], v[132:135], v[76:79]
	global_load_dwordx4 v[128:131], v[248:249], off
	global_load_dwordx4 v[132:135], v[248:249], off offset:256
	s_waitcnt vmcnt(6)
	s_barrier
	s_add_i32 s9, s8, 5
	s_lshl_b32 s96, s9, 13
	s_add_i32 m0, vcc_lo, 16384
	v_lshl_add_u64 v[160:161], v[188:189], 0, s[96:97]
	global_load_lds_dwordx4 v[160:161], off
	global_load_lds_dwordx4 v[160:161], off offset:1024
	ds_read_b128 v[196:199], v246 offset:0
	ds_read_b128 v[200:203], v162 offset:0
	ds_read_b128 v[204:207], v246 offset:2048
	ds_read_b128 v[242:245], v162 offset:2048
	s_add_i32 s9, s8, 5
	s_lshl_b32 s96, s9, 11
	v_lshl_add_u64 v[248:249], v[184:185], 0, s[96:97]
	v_lshl_add_u64 v[250:251], v[186:187], 0, s[96:97]
	s_waitcnt vmcnt(6) lgkmcnt(3)
	v_mfma_f32_16x16x32_bf16 v[112:115], v[196:199], v[144:147], v[112:115]
	v_mfma_f32_16x16x32_bf16 v[120:123], v[196:199], v[148:151], v[120:123]
	ds_read_b128 v[196:199], v246 offset:4096
	s_waitcnt lgkmcnt(3)
	v_mfma_f32_16x16x32_bf16 v[116:119], v[200:203], v[144:147], v[116:119]
	v_mfma_f32_16x16x32_bf16 v[124:127], v[200:203], v[148:151], v[124:127]
	ds_read_b128 v[200:203], v162 offset:4096
	s_waitcnt lgkmcnt(3)
	v_mfma_f32_16x16x32_bf16 v[96:99], v[204:207], v[144:147], v[96:99]
	v_mfma_f32_16x16x32_bf16 v[104:107], v[204:207], v[148:151], v[104:107]
	ds_read_b128 v[204:207], v246 offset:6144
	s_waitcnt lgkmcnt(3)
	v_mfma_f32_16x16x32_bf16 v[100:103], v[242:245], v[144:147], v[100:103]
	v_mfma_f32_16x16x32_bf16 v[108:111], v[242:245], v[148:151], v[108:111]
	ds_read_b128 v[242:245], v162 offset:6144
	s_waitcnt lgkmcnt(3)
	v_mfma_f32_16x16x32_bf16 v[80:83], v[196:199], v[144:147], v[80:83]
	v_mfma_f32_16x16x32_bf16 v[88:91], v[196:199], v[148:151], v[88:91]
	s_waitcnt lgkmcnt(2)
	v_mfma_f32_16x16x32_bf16 v[84:87], v[200:203], v[144:147], v[84:87]
	v_mfma_f32_16x16x32_bf16 v[92:95], v[200:203], v[148:151], v[92:95]
	s_waitcnt lgkmcnt(1)
	v_mfma_f32_16x16x32_bf16 v[64:67], v[204:207], v[144:147], v[64:67]
	v_mfma_f32_16x16x32_bf16 v[72:75], v[204:207], v[148:151], v[72:75]
	s_waitcnt lgkmcnt(0)
	v_mfma_f32_16x16x32_bf16 v[68:71], v[242:245], v[144:147], v[68:71]
	v_mfma_f32_16x16x32_bf16 v[76:79], v[242:245], v[148:151], v[76:79]
	global_load_dwordx4 v[144:147], v[248:249], off
	global_load_dwordx4 v[148:151], v[248:249], off offset:256
	s_waitcnt vmcnt(6)
	s_barrier
	s_add_i32 s9, s8, 6
	s_lshl_b32 s96, s9, 13
	s_mov_b32 m0, vcc_lo
	v_lshl_add_u64 v[160:161], v[188:189], 0, s[96:97]
	global_load_lds_dwordx4 v[160:161], off
	global_load_lds_dwordx4 v[160:161], off offset:1024
	ds_read_b128 v[196:199], v246 offset:8192
	ds_read_b128 v[200:203], v162 offset:8192
	ds_read_b128 v[204:207], v246 offset:10240
	ds_read_b128 v[242:245], v162 offset:10240
	s_add_i32 s9, s8, 6
	s_lshl_b32 s96, s9, 11
	v_lshl_add_u64 v[248:249], v[184:185], 0, s[96:97]
	v_lshl_add_u64 v[250:251], v[186:187], 0, s[96:97]
	s_waitcnt vmcnt(6) lgkmcnt(3)
	v_mfma_f32_16x16x32_bf16 v[112:115], v[196:199], v[128:131], v[112:115]
	v_mfma_f32_16x16x32_bf16 v[120:123], v[196:199], v[132:135], v[120:123]
	ds_read_b128 v[196:199], v246 offset:12288
	s_waitcnt lgkmcnt(3)
	v_mfma_f32_16x16x32_bf16 v[116:119], v[200:203], v[128:131], v[116:119]
	v_mfma_f32_16x16x32_bf16 v[124:127], v[200:203], v[132:135], v[124:127]
	ds_read_b128 v[200:203], v162 offset:12288
	s_waitcnt lgkmcnt(3)
	v_mfma_f32_16x16x32_bf16 v[96:99], v[204:207], v[128:131], v[96:99]
	v_mfma_f32_16x16x32_bf16 v[104:107], v[204:207], v[132:135], v[104:107]
	ds_read_b128 v[204:207], v246 offset:14336
	s_waitcnt lgkmcnt(3)
	v_mfma_f32_16x16x32_bf16 v[100:103], v[242:245], v[128:131], v[100:103]
	v_mfma_f32_16x16x32_bf16 v[108:111], v[242:245], v[132:135], v[108:111]
	ds_read_b128 v[242:245], v162 offset:14336
	s_waitcnt lgkmcnt(3)
	v_mfma_f32_16x16x32_bf16 v[80:83], v[196:199], v[128:131], v[80:83]
	v_mfma_f32_16x16x32_bf16 v[88:91], v[196:199], v[132:135], v[88:91]
	s_waitcnt lgkmcnt(2)
	v_mfma_f32_16x16x32_bf16 v[84:87], v[200:203], v[128:131], v[84:87]
	v_mfma_f32_16x16x32_bf16 v[92:95], v[200:203], v[132:135], v[92:95]
	s_waitcnt lgkmcnt(1)
	v_mfma_f32_16x16x32_bf16 v[64:67], v[204:207], v[128:131], v[64:67]
	v_mfma_f32_16x16x32_bf16 v[72:75], v[204:207], v[132:135], v[72:75]
	s_waitcnt lgkmcnt(0)
	v_mfma_f32_16x16x32_bf16 v[68:71], v[242:245], v[128:131], v[68:71]
	v_mfma_f32_16x16x32_bf16 v[76:79], v[242:245], v[132:135], v[76:79]
	global_load_dwordx4 v[128:131], v[248:249], off
	global_load_dwordx4 v[132:135], v[248:249], off offset:256
	s_waitcnt vmcnt(6)
	s_barrier
	s_add_i32 s9, s8, 7
	s_lshl_b32 s96, s9, 13
	s_add_i32 m0, vcc_lo, 8192
	v_lshl_add_u64 v[160:161], v[188:189], 0, s[96:97]
	global_load_lds_dwordx4 v[160:161], off
	global_load_lds_dwordx4 v[160:161], off offset:1024
	ds_read_b128 v[196:199], v246 offset:16384
	ds_read_b128 v[200:203], v162 offset:16384
	ds_read_b128 v[204:207], v246 offset:18432
	ds_read_b128 v[242:245], v162 offset:18432
	s_add_i32 s9, s8, 7
	s_lshl_b32 s96, s9, 11
	v_lshl_add_u64 v[248:249], v[184:185], 0, s[96:97]
	v_lshl_add_u64 v[250:251], v[186:187], 0, s[96:97]
	s_waitcnt vmcnt(6) lgkmcnt(3)
	v_mfma_f32_16x16x32_bf16 v[112:115], v[196:199], v[144:147], v[112:115]
	v_mfma_f32_16x16x32_bf16 v[120:123], v[196:199], v[148:151], v[120:123]
	ds_read_b128 v[196:199], v246 offset:20480
	s_waitcnt lgkmcnt(3)
	v_mfma_f32_16x16x32_bf16 v[116:119], v[200:203], v[144:147], v[116:119]
	v_mfma_f32_16x16x32_bf16 v[124:127], v[200:203], v[148:151], v[124:127]
	ds_read_b128 v[200:203], v162 offset:20480
	s_waitcnt lgkmcnt(3)
	v_mfma_f32_16x16x32_bf16 v[96:99], v[204:207], v[144:147], v[96:99]
	v_mfma_f32_16x16x32_bf16 v[104:107], v[204:207], v[148:151], v[104:107]
	ds_read_b128 v[204:207], v246 offset:22528
	s_waitcnt lgkmcnt(3)
	v_mfma_f32_16x16x32_bf16 v[100:103], v[242:245], v[144:147], v[100:103]
	v_mfma_f32_16x16x32_bf16 v[108:111], v[242:245], v[148:151], v[108:111]
	ds_read_b128 v[242:245], v162 offset:22528
	s_waitcnt lgkmcnt(3)
	v_mfma_f32_16x16x32_bf16 v[80:83], v[196:199], v[144:147], v[80:83]
	v_mfma_f32_16x16x32_bf16 v[88:91], v[196:199], v[148:151], v[88:91]
	s_waitcnt lgkmcnt(2)
	v_mfma_f32_16x16x32_bf16 v[84:87], v[200:203], v[144:147], v[84:87]
	v_mfma_f32_16x16x32_bf16 v[92:95], v[200:203], v[148:151], v[92:95]
	s_waitcnt lgkmcnt(1)
	v_mfma_f32_16x16x32_bf16 v[64:67], v[204:207], v[144:147], v[64:67]
	v_mfma_f32_16x16x32_bf16 v[72:75], v[204:207], v[148:151], v[72:75]
	s_waitcnt lgkmcnt(0)
	v_mfma_f32_16x16x32_bf16 v[68:71], v[242:245], v[144:147], v[68:71]
	v_mfma_f32_16x16x32_bf16 v[76:79], v[242:245], v[148:151], v[76:79]
	global_load_dwordx4 v[144:147], v[248:249], off
	global_load_dwordx4 v[148:151], v[248:249], off offset:256
	s_waitcnt vmcnt(6)
	s_barrier
	s_add_i32 s8, s8, 6
	s_cmp_lt_u32 s8, 84
	s_cbranch_scc1 .Lg16_downh_k
	s_lshl_b32 s16, s7, 8
	s_lshl_b32 s18, s6, 9
	v_readlane_b32 s12, v253, 46
	v_readlane_b32 s13, v253, 47
	s_add_i32 s17, s16, 0xffff8000
	s_cmpk_lt_u32 s7, 0x80
	s_cselect_b32 s12, s12, s62
	s_cselect_b32 s13, s13, s63
	s_cselect_b32 s16, s16, s17
	s_mov_b32 s17, 0
	s_lshl_b64 s[16:17], s[16:17], 12
	s_add_u32 s16, s16, s18
	s_addc_u32 s17, s17, 0
	s_add_u32 s12, s12, s16
	s_addc_u32 s13, s13, s17
	v_lshlrev_b32_e32 v167, 12, v179
	global_load_dword v163, v167, s[12:13]
	global_load_dword v164, v167, s[12:13] offset:128
	global_load_dword v165, v167, s[12:13] offset:256
	global_load_dword v166, v167, s[12:13] offset:384
	s_mov_b32 s96, 0xac000
	s_add_i32 m0, vcc_lo, 16384
	v_lshl_add_u64 v[160:161], v[188:189], 0, s[96:97]
	global_load_lds_dwordx4 v[160:161], off
	global_load_lds_dwordx4 v[160:161], off offset:1024
	ds_read_b128 v[196:199], v246 offset:0
	ds_read_b128 v[200:203], v162 offset:0
	ds_read_b128 v[204:207], v246 offset:2048
	ds_read_b128 v[242:245], v162 offset:2048
	s_mov_b32 s96, 0x2b000
	v_lshl_add_u64 v[248:249], v[184:185], 0, s[96:97]
	v_lshl_add_u64 v[250:251], v[186:187], 0, s[96:97]
	s_waitcnt vmcnt(10) lgkmcnt(3)
	v_mfma_f32_16x16x32_bf16 v[112:115], v[196:199], v[128:131], v[112:115]
	v_mfma_f32_16x16x32_bf16 v[120:123], v[196:199], v[132:135], v[120:123]
	ds_read_b128 v[196:199], v246 offset:4096
	s_waitcnt lgkmcnt(3)
	v_mfma_f32_16x16x32_bf16 v[116:119], v[200:203], v[128:131], v[116:119]
	v_mfma_f32_16x16x32_bf16 v[124:127], v[200:203], v[132:135], v[124:127]
	ds_read_b128 v[200:203], v162 offset:4096
	s_waitcnt lgkmcnt(3)
	v_mfma_f32_16x16x32_bf16 v[96:99], v[204:207], v[128:131], v[96:99]
	v_mfma_f32_16x16x32_bf16 v[104:107], v[204:207], v[132:135], v[104:107]
	ds_read_b128 v[204:207], v246 offset:6144
	s_waitcnt lgkmcnt(3)
	v_mfma_f32_16x16x32_bf16 v[100:103], v[242:245], v[128:131], v[100:103]
	v_mfma_f32_16x16x32_bf16 v[108:111], v[242:245], v[132:135], v[108:111]
	ds_read_b128 v[242:245], v162 offset:6144
	s_waitcnt lgkmcnt(3)
	v_mfma_f32_16x16x32_bf16 v[80:83], v[196:199], v[128:131], v[80:83]
	v_mfma_f32_16x16x32_bf16 v[88:91], v[196:199], v[132:135], v[88:91]
	s_waitcnt lgkmcnt(2)
	v_mfma_f32_16x16x32_bf16 v[84:87], v[200:203], v[128:131], v[84:87]
	v_mfma_f32_16x16x32_bf16 v[92:95], v[200:203], v[132:135], v[92:95]
	s_waitcnt lgkmcnt(1)
	v_mfma_f32_16x16x32_bf16 v[64:67], v[204:207], v[128:131], v[64:67]
	v_mfma_f32_16x16x32_bf16 v[72:75], v[204:207], v[132:135], v[72:75]
	s_waitcnt lgkmcnt(0)
	v_mfma_f32_16x16x32_bf16 v[68:71], v[242:245], v[128:131], v[68:71]
	v_mfma_f32_16x16x32_bf16 v[76:79], v[242:245], v[132:135], v[76:79]
	global_load_dwordx4 v[128:131], v[248:249], off
	global_load_dwordx4 v[132:135], v[248:249], off offset:256
	s_waitcnt vmcnt(10)
	s_barrier
	s_mov_b32 s96, 0xae000
	s_mov_b32 m0, vcc_lo
	v_lshl_add_u64 v[160:161], v[188:189], 0, s[96:97]
	global_load_lds_dwordx4 v[160:161], off
	global_load_lds_dwordx4 v[160:161], off offset:1024
	ds_read_b128 v[196:199], v246 offset:8192
	ds_read_b128 v[200:203], v162 offset:8192
	ds_read_b128 v[204:207], v246 offset:10240
	ds_read_b128 v[242:245], v162 offset:10240
	s_mov_b32 s96, 0x2b800
	v_lshl_add_u64 v[248:249], v[184:185], 0, s[96:97]
	v_lshl_add_u64 v[250:251], v[186:187], 0, s[96:97]
	s_waitcnt vmcnt(10) lgkmcnt(3)
	v_mfma_f32_16x16x32_bf16 v[112:115], v[196:199], v[144:147], v[112:115]
	v_mfma_f32_16x16x32_bf16 v[120:123], v[196:199], v[148:151], v[120:123]
	ds_read_b128 v[196:199], v246 offset:12288
	s_waitcnt lgkmcnt(3)
	v_mfma_f32_16x16x32_bf16 v[116:119], v[200:203], v[144:147], v[116:119]
	v_mfma_f32_16x16x32_bf16 v[124:127], v[200:203], v[148:151], v[124:127]
	ds_read_b128 v[200:203], v162 offset:12288
	s_waitcnt lgkmcnt(3)
	v_mfma_f32_16x16x32_bf16 v[96:99], v[204:207], v[144:147], v[96:99]
	v_mfma_f32_16x16x32_bf16 v[104:107], v[204:207], v[148:151], v[104:107]
	ds_read_b128 v[204:207], v246 offset:14336
	s_waitcnt lgkmcnt(3)
	v_mfma_f32_16x16x32_bf16 v[100:103], v[242:245], v[144:147], v[100:103]
	v_mfma_f32_16x16x32_bf16 v[108:111], v[242:245], v[148:151], v[108:111]
	ds_read_b128 v[242:245], v162 offset:14336
	s_waitcnt lgkmcnt(3)
	v_mfma_f32_16x16x32_bf16 v[80:83], v[196:199], v[144:147], v[80:83]
	v_mfma_f32_16x16x32_bf16 v[88:91], v[196:199], v[148:151], v[88:91]
	s_waitcnt lgkmcnt(2)
	v_mfma_f32_16x16x32_bf16 v[84:87], v[200:203], v[144:147], v[84:87]
	v_mfma_f32_16x16x32_bf16 v[92:95], v[200:203], v[148:151], v[92:95]
	s_waitcnt lgkmcnt(1)
	v_mfma_f32_16x16x32_bf16 v[64:67], v[204:207], v[144:147], v[64:67]
	v_mfma_f32_16x16x32_bf16 v[72:75], v[204:207], v[148:151], v[72:75]
	s_waitcnt lgkmcnt(0)
	v_mfma_f32_16x16x32_bf16 v[68:71], v[242:245], v[144:147], v[68:71]
	v_mfma_f32_16x16x32_bf16 v[76:79], v[242:245], v[148:151], v[76:79]
	global_load_dwordx4 v[144:147], v[248:249], off
	global_load_dwordx4 v[148:151], v[248:249], off offset:256
	s_waitcnt vmcnt(6)
	s_barrier
	ds_read_b128 v[196:199], v246 offset:16384
	ds_read_b128 v[200:203], v162 offset:16384
	ds_read_b128 v[204:207], v246 offset:18432
	ds_read_b128 v[242:245], v162 offset:18432
	s_waitcnt vmcnt(4) lgkmcnt(3)
	v_mfma_f32_16x16x32_bf16 v[112:115], v[196:199], v[128:131], v[112:115]
	v_mfma_f32_16x16x32_bf16 v[120:123], v[196:199], v[132:135], v[120:123]
	ds_read_b128 v[196:199], v246 offset:20480
	s_waitcnt lgkmcnt(3)
	v_mfma_f32_16x16x32_bf16 v[116:119], v[200:203], v[128:131], v[116:119]
	v_mfma_f32_16x16x32_bf16 v[124:127], v[200:203], v[132:135], v[124:127]
	ds_read_b128 v[200:203], v162 offset:20480
	s_waitcnt lgkmcnt(3)
	v_mfma_f32_16x16x32_bf16 v[96:99], v[204:207], v[128:131], v[96:99]
	v_mfma_f32_16x16x32_bf16 v[104:107], v[204:207], v[132:135], v[104:107]
	ds_read_b128 v[204:207], v246 offset:22528
	s_waitcnt lgkmcnt(3)
	v_mfma_f32_16x16x32_bf16 v[100:103], v[242:245], v[128:131], v[100:103]
	v_mfma_f32_16x16x32_bf16 v[108:111], v[242:245], v[132:135], v[108:111]
	ds_read_b128 v[242:245], v162 offset:22528
	s_waitcnt lgkmcnt(3)
	v_mfma_f32_16x16x32_bf16 v[80:83], v[196:199], v[128:131], v[80:83]
	v_mfma_f32_16x16x32_bf16 v[88:91], v[196:199], v[132:135], v[88:91]
	s_waitcnt lgkmcnt(2)
	v_mfma_f32_16x16x32_bf16 v[84:87], v[200:203], v[128:131], v[84:87]
	v_mfma_f32_16x16x32_bf16 v[92:95], v[200:203], v[132:135], v[92:95]
	s_waitcnt lgkmcnt(1)
	v_mfma_f32_16x16x32_bf16 v[64:67], v[204:207], v[128:131], v[64:67]
	v_mfma_f32_16x16x32_bf16 v[72:75], v[204:207], v[132:135], v[72:75]
	s_waitcnt lgkmcnt(0)
	v_mfma_f32_16x16x32_bf16 v[68:71], v[242:245], v[128:131], v[68:71]
	v_mfma_f32_16x16x32_bf16 v[76:79], v[242:245], v[132:135], v[76:79]
	s_waitcnt vmcnt(2)
	s_barrier
	ds_read_b128 v[196:199], v246 offset:0
	ds_read_b128 v[200:203], v162 offset:0
	ds_read_b128 v[204:207], v246 offset:2048
	ds_read_b128 v[242:245], v162 offset:2048
	s_waitcnt vmcnt(0) lgkmcnt(3)
	v_mfma_f32_16x16x32_bf16 v[112:115], v[196:199], v[144:147], v[112:115]
	v_mfma_f32_16x16x32_bf16 v[120:123], v[196:199], v[148:151], v[120:123]
	ds_read_b128 v[196:199], v246 offset:4096
	s_waitcnt lgkmcnt(3)
	v_mfma_f32_16x16x32_bf16 v[116:119], v[200:203], v[144:147], v[116:119]
	v_mfma_f32_16x16x32_bf16 v[124:127], v[200:203], v[148:151], v[124:127]
	ds_read_b128 v[200:203], v162 offset:4096
	s_waitcnt lgkmcnt(3)
	v_mfma_f32_16x16x32_bf16 v[96:99], v[204:207], v[144:147], v[96:99]
	v_mfma_f32_16x16x32_bf16 v[104:107], v[204:207], v[148:151], v[104:107]
	ds_read_b128 v[204:207], v246 offset:6144
	s_waitcnt lgkmcnt(3)
	v_mfma_f32_16x16x32_bf16 v[100:103], v[242:245], v[144:147], v[100:103]
	v_mfma_f32_16x16x32_bf16 v[108:111], v[242:245], v[148:151], v[108:111]
	ds_read_b128 v[242:245], v162 offset:6144
	s_waitcnt lgkmcnt(3)
	v_mfma_f32_16x16x32_bf16 v[80:83], v[196:199], v[144:147], v[80:83]
	v_mfma_f32_16x16x32_bf16 v[88:91], v[196:199], v[148:151], v[88:91]
	s_waitcnt lgkmcnt(2)
	v_mfma_f32_16x16x32_bf16 v[84:87], v[200:203], v[144:147], v[84:87]
	v_mfma_f32_16x16x32_bf16 v[92:95], v[200:203], v[148:151], v[92:95]
	s_waitcnt lgkmcnt(1)
	v_mfma_f32_16x16x32_bf16 v[64:67], v[204:207], v[144:147], v[64:67]
	v_mfma_f32_16x16x32_bf16 v[72:75], v[204:207], v[148:151], v[72:75]
	s_waitcnt lgkmcnt(0)
	v_mfma_f32_16x16x32_bf16 v[68:71], v[242:245], v[144:147], v[68:71]
	v_mfma_f32_16x16x32_bf16 v[76:79], v[242:245], v[148:151], v[76:79]
	s_barrier
	s_nop 7
	s_nop 1
	s_waitcnt vmcnt(0)
	s_waitcnt vmcnt(0)
	v_and_b32_e32 v188, 63, v179
	v_lshrrev_b32_e32 v189, 6, v179
	v_mul_u32_u24_e32 v249, 0x2400, v189
	v_mov_b32_e32 v250, v249
	v_and_b32_e32 v251, 15, v188
	v_mul_u32_u24_e32 v251, 0x110, v251
	v_add_u32_e32 v249, v249, v251
	v_lshrrev_b32_e32 v251, 4, v188
	v_lshl_add_u32 v249, v251, 5, v249
	v_lshrrev_b32_e32 v237, 4, v188
	v_mul_u32_u24_e32 v251, 0x110, v237
	v_add_u32_e32 v250, v250, v251
	v_and_b32_e32 v251, 15, v188
	v_lshlrev_b32_e32 v251, 4, v251
	v_add_u32_e32 v250, v250, v251
	v_lshl_add_u32 v237, v189, 6, v237
	v_lshl_add_u32 v237, v237, 12, v251
	v_add_u32_e32 v238, 16384, v237
	v_add_u32_e32 v239, 32768, v237
	v_add_u32_e32 v240, 49152, v237
	v_add_u32_e32 v241, 65536, v237
	v_add_u32_e32 v242, 81920, v237
	v_add_u32_e32 v243, 98304, v237
	v_add_u32_e32 v248, 114688, v237
	s_lshl_b32 s16, s7, 8
	s_lshl_b32 s18, s6, 9
	s_lshr_b32 s19, s7, 4
	v_readlane_b32 s12, v253, 46
	v_readlane_b32 s13, v253, 47
	v_readlane_b32 s14, v253, 46
	v_readlane_b32 s15, v253, 47
	s_add_i32 s17, s16, 0xffff8000
	s_cmpk_lt_u32 s7, 0x80
	s_cselect_b32 s12, s12, s62
	s_cselect_b32 s13, s13, s63
	s_cselect_b32 s14, s14, s62
	s_cselect_b32 s15, s15, s63
	s_cselect_b32 s19, s19, 8
	s_cselect_b32 s16, s16, s17
	s_mov_b32 s17, 0
	s_lshl_b64 s[16:17], s[16:17], 12
	s_add_u32 s16, s16, s18
	s_addc_u32 s17, s17, 0
	s_add_u32 s12, s12, s16
	s_addc_u32 s13, s13, s17
	s_add_u32 s14, s14, s16
	s_addc_u32 s15, s15, s17
	s_mul_i32 s19, s19, 0x6000
	s_add_u32 s20, s0, s19
	s_addc_u32 s21, s1, 0
	s_add_u32 s20, s20, s18
	s_addc_u32 s21, s21, 0
	s_cmp_eq_u32 s101, 1
	s_cbranch_scc0 .Lre_downh_h0
	s_add_u32 s12, s12, 0x20000
	s_addc_u32 s13, s13, 0
	s_add_u32 s14, s14, 0x20000
	s_addc_u32 s15, s15, 0
